# store deferral (loads before the preceding store, operands copied) extended to final norm and phase 6 epilogues
# baseline (speedup 1.0000x reference)
; __device__ __forceinline__ void gdn_out_phase(const Params& p, char* smem, int bid, int nblk) {
;     ...
;   for (int item = bid; item < 2048; item += nblk) {
;     const int n = item & 127, bh = item >> 7, b = bh >> 2, h = bh & 3;
;     {
;       u32x4 st[6];
; #pragma unroll
;       for (int k = 0; k < 4; ++k) st[k] = *(const u32x4*)(gqd + (size_t)item * 16384 + (tid + 256 * k) * 16);
; #pragma unroll
;       for (int k = 0; k < 2; ++k) st[4 + k] = *(const u32x4*)(gat + (size_t)item * 8192 + (tid + 256 * k) * 16);
; #pragma unroll
;       for (int k = 0; k < 4; ++k) { const int pc = tid + 256 * k; char* d = QDl + (pc >> 4) * 264 + (pc & 15) * 16;
;         *(uint2*)d = uint2{st[k][0], st[k][1]}; *(uint2*)(d + 8) = uint2{st[k][2], st[k][3]}; }
; #pragma unroll
;       for (int k = 0; k < 2; ++k) { const int pc = tid + 256 * k; char* d = ATl + (pc >> 3) * 136 + (pc & 7) * 16;
;         *(uint2*)d = uint2{st[4 + k][0], st[4 + k][1]}; *(uint2*)(d + 8) = uint2{st[4 + k][2], st[4 + k][3]}; }
;     }
;     bf16x8 sb[8], vb[4];
; #pragma unroll
;     for (int f = 0; f < 8; ++f) sb[f] = __builtin_bit_cast(bf16x8, sbg[((size_t)(item * 4 + wid) * 8 + f) * 64 + lane]);
; #pragma unroll
;     for (int f = 0; f < 4; ++f) vb[f] = __builtin_bit_cast(bf16x8, vbg[((size_t)(item * 4 + wid) * 4 + f) * 64 + lane]);
;     __syncthreads();
;     f32x16 ao[2];
; #pragma unroll
;     for (int r = 0; r < 16; ++r) { ao[0][r] = 0.f; ao[1][r] = 0.f; }
; #pragma unroll
;     for (int T = 0; T < 4; ++T)
; #pragma unroll
;       for (int s = 0; s < 2; ++s) {
;         const int cb = (32 * T + 16 * s + 4 * hi) * 2;
; #pragma unroll
;         for (int it = 0; it < 2; ++it) {
;           const char* qp = QDl + (32 * it + r32) * 264 + cb;
;           ao[it] = __builtin_amdgcn_mfma_f32_32x32x16_bf16(mk8(lds64(qp), lds64(qp + 16)), sb[T * 2 + s], ao[it], 0, 0, 0);
;         }
;       }
; #pragma unroll
;     for (int it2 = 0; it2 < 2; ++it2)
; #pragma unroll
;       for (int it = 0; it <= it2; ++it)
; #pragma unroll
;         for (int s = 0; s < 2; ++s) {
;           const char* ap = ATl + (32 * it2 + r32) * 136 + (32 * it + 16 * s + 4 * hi) * 2;
;           ao[it2] = __builtin_amdgcn_mfma_f32_32x32x16_bf16(mk8(lds64(ap), lds64(ap + 16)), vb[it * 2 + s], ao[it2], 0, 0, 0);
;         }
; #pragma unroll
;     for (int it = 0; it < 2; ++it)
; #pragma unroll
.LBB0_1266:
	v_lshl_add_u64 v[24:25], s[76:77], 0, v[94:95]
	v_lshl_add_u64 v[26:27], s[76:77], 0, v[96:97]
	v_lshl_add_u64 v[30:31], s[76:77], 0, v[98:99]
	v_lshl_add_u64 v[28:29], s[76:77], 0, v[100:101]
	v_lshl_add_u64 v[32:33], s[76:77], 0, v[90:91]
	v_lshl_add_u64 v[34:35], s[76:77], 0, v[92:93]
	global_load_dwordx4 v[0:3], v[24:25], off
	global_load_dwordx4 v[4:7], v[26:27], off
	global_load_dwordx4 v[8:11], v[30:31], off
	global_load_dwordx4 v[12:15], v[28:29], off
	global_load_dwordx4 v[16:19], v[32:33], off
	global_load_dwordx4 v[20:23], v[34:35], off
	v_ashrrev_i32_e32 v89, 31, v88
	v_lshlrev_b64 v[24:25], 13, v[88:89]
	v_lshl_add_u64 v[24:25], v[82:83], 0, v[24:25]
	global_load_dwordx4 v[68:71], v[24:25], off
	global_load_dwordx4 v[60:63], v[24:25], off offset:1024
	global_load_dwordx4 v[52:55], v[24:25], off offset:2048
	global_load_dwordx4 v[48:51], v[24:25], off offset:3072
	v_lshlrev_b64 v[26:27], 12, v[88:89]
	v_add_co_u32_e32 v24, vcc, s2, v24
	v_lshl_add_u64 v[26:27], v[84:85], 0, v[26:27]
	s_nop 0
	v_addc_co_u32_e32 v25, vcc, 0, v25, vcc
	s_and_b32 s4, s12, 0xffffe000
	s_and_b32 s16, s10, 0x1fc0
	global_load_dwordx4 v[44:47], v[26:27], off
	global_load_dwordx4 v[40:43], v[26:27], off offset:1024
	global_load_dwordx4 v[36:39], v[26:27], off offset:2048
	global_load_dwordx4 v[32:35], v[26:27], off offset:3072
	global_load_dwordx4 v[76:79], v[24:25], off
	global_load_dwordx4 v[72:75], v[24:25], off offset:1024
	global_load_dwordx4 v[64:67], v[24:25], off offset:2048
	global_load_dwordx4 v[56:59], v[24:25], off offset:3072
	s_or_b32 s16, s4, s16
	v_add_u32_e32 v28, s16, v122
	s_and_b32 s17, s15, 0x180
	v_ashrrev_i32_e32 v29, 31, v28
	v_ashrrev_i32_e32 v26, 3, v28
	s_lshl_b32 s4, s17, 1
	s_lshr_b32 s17, s17, 5
	v_lshlrev_b64 v[24:25], 10, v[28:29]
	v_and_b32_e32 v26, 0xffffffe0, v26
	v_lshlrev_b32_e32 v27, 6, v28
	v_lshl_add_u64 v[24:25], s[0:1], 0, v[24:25]
	v_or3_b32 v26, s17, v26, v123
	v_and_b32_e32 v80, 0x3fc0, v27
	v_lshl_add_u64 v[24:25], v[24:25], 0, s[4:5]
	v_ashrrev_i32_e32 v27, 31, v26
	v_lshl_add_u64 v[114:115], v[24:25], 0, v[102:103]
	v_lshlrev_b64 v[24:25], 14, v[26:27]
	v_lshl_add_u64 v[24:25], s[62:63], 0, v[24:25]
	v_lshl_add_u64 v[112:113], v[24:25], 0, v[80:81]
	v_lshl_add_u64 v[116:117], v[112:113], 0, v[104:105]
	v_lshl_add_u64 v[118:119], v[112:113], 0, v[106:107]
	v_lshl_add_u64 v[120:121], v[112:113], 0, v[108:109]
	s_add_i32 s15, s15, s34
	s_add_i32 s10, s10, s11
	s_add_i32 s12, s12, s13
	v_lshl_add_u64 v[90:91], v[90:91], 0, s[6:7]
	v_lshl_add_u64 v[92:93], v[92:93], 0, s[6:7]
	v_lshl_add_u64 v[94:95], v[94:95], 0, s[8:9]
	v_lshl_add_u64 v[96:97], v[96:97], 0, s[8:9]
	v_lshl_add_u64 v[98:99], v[98:99], 0, s[8:9]
	v_lshl_add_u64 v[100:101], v[100:101], 0, s[8:9]
	v_add_u32_e32 v88, s3, v88
	s_cmpk_lt_i32 s15, 0x800
	s_waitcnt vmcnt(0)
	ds_write2_b64 v126, v[0:1], v[2:3] offset1:1
	ds_write2_b64 v127, v[4:5], v[6:7] offset1:1
	ds_write2_b64 v128, v[8:9], v[10:11] offset1:1
	ds_write2_b64 v129, v[12:13], v[14:15] offset1:1
	ds_write2_b64 v130, v[16:17], v[18:19] offset1:1
	ds_write2_b64 v131, v[20:21], v[22:23] offset1:1
	s_waitcnt lgkmcnt(0)
	s_barrier
	ds_read2_b64 v[0:3], v132 offset1:2
	s_waitcnt lgkmcnt(0)
	v_mfma_f32_32x32x16_bf16 v[16:31], v[0:3], v[68:71], 0
	ds_read2_b64 v[0:3], v135 offset0:32 offset1:34
	s_waitcnt lgkmcnt(0)
	v_mfma_f32_32x32x16_bf16 v[0:15], v[0:3], v[68:71], 0
	ds_read2_b64 v[68:71], v132 offset0:4 offset1:6
	s_waitcnt lgkmcnt(0)
	v_mfma_f32_32x32x16_bf16 v[16:31], v[68:71], v[60:63], v[16:31]
	ds_read2_b64 v[68:71], v135 offset0:36 offset1:38
	s_waitcnt lgkmcnt(0)
	v_mfma_f32_32x32x16_bf16 v[0:15], v[68:71], v[60:63], v[0:15]
	ds_read2_b64 v[60:63], v132 offset0:8 offset1:10
	s_waitcnt lgkmcnt(0)
	v_mfma_f32_32x32x16_bf16 v[16:31], v[60:63], v[52:55], v[16:31]
	ds_read2_b64 v[60:63], v135 offset0:40 offset1:42
	s_waitcnt lgkmcnt(0)
	v_mfma_f32_32x32x16_bf16 v[0:15], v[60:63], v[52:55], v[0:15]
	ds_read2_b64 v[52:55], v132 offset0:12 offset1:14
	s_waitcnt lgkmcnt(0)
	v_mfma_f32_32x32x16_bf16 v[16:31], v[52:55], v[48:51], v[16:31]
	ds_read2_b64 v[52:55], v135 offset0:44 offset1:46
	s_waitcnt lgkmcnt(0)
	v_mfma_f32_32x32x16_bf16 v[0:15], v[52:55], v[48:51], v[0:15]
	ds_read2_b64 v[48:51], v132 offset0:16 offset1:18
	s_waitcnt lgkmcnt(0)
	v_mfma_f32_32x32x16_bf16 v[16:31], v[48:51], v[76:79], v[16:31]
	ds_read2_b64 v[48:51], v135 offset0:48 offset1:50
	s_waitcnt lgkmcnt(0)
	v_mfma_f32_32x32x16_bf16 v[0:15], v[48:51], v[76:79], v[0:15]
	ds_read2_b64 v[48:51], v132 offset0:20 offset1:22
	s_waitcnt lgkmcnt(0)
	v_mfma_f32_32x32x16_bf16 v[16:31], v[48:51], v[72:75], v[16:31]
	ds_read2_b64 v[48:51], v135 offset0:52 offset1:54
	s_waitcnt lgkmcnt(0)
	v_mfma_f32_32x32x16_bf16 v[0:15], v[48:51], v[72:75], v[0:15]
	ds_read2_b64 v[48:51], v132 offset0:24 offset1:26
	s_waitcnt lgkmcnt(0)
	v_mfma_f32_32x32x16_bf16 v[16:31], v[48:51], v[64:67], v[16:31]
	ds_read2_b64 v[48:51], v135 offset0:56 offset1:58
	s_waitcnt lgkmcnt(0)
	v_mfma_f32_32x32x16_bf16 v[0:15], v[48:51], v[64:67], v[0:15]
	ds_read2_b64 v[48:51], v132 offset0:28 offset1:30
	s_waitcnt lgkmcnt(0)
	v_mfma_f32_32x32x16_bf16 v[16:31], v[48:51], v[56:59], v[16:31]
	ds_read2_b64 v[48:51], v135 offset0:60 offset1:62
	s_waitcnt lgkmcnt(0)
	v_mfma_f32_32x32x16_bf16 v[0:15], v[48:51], v[56:59], v[0:15]
	ds_read2_b64 v[48:51], v136 offset0:64 offset1:66
	s_waitcnt lgkmcnt(0)
	v_mfma_f32_32x32x16_bf16 v[16:31], v[48:51], v[44:47], v[16:31]
	ds_read2_b64 v[48:51], v137 offset0:96 offset1:98
	s_waitcnt lgkmcnt(0)
	v_mfma_f32_32x32x16_bf16 v[0:15], v[48:51], v[44:47], v[0:15]
	ds_read2_b64 v[44:47], v136 offset0:68 offset1:70
	s_waitcnt lgkmcnt(0)
	v_mfma_f32_32x32x16_bf16 v[16:31], v[44:47], v[40:43], v[16:31]
	ds_read2_b64 v[44:47], v137 offset0:100 offset1:102
	s_waitcnt lgkmcnt(0)
	v_mfma_f32_32x32x16_bf16 v[0:15], v[44:47], v[40:43], v[0:15]
	ds_read2_b64 v[40:43], v137 offset0:104 offset1:106
	ds_read2_b64 v[44:47], v137 offset0:108 offset1:110
	s_nop 6
	ds_write2_b32 v138, v16, v17 offset1:132
	ds_write2_b32 v139, v18, v19 offset0:8 offset1:140
	ds_write2_b32 v140, v20, v21 offset0:32 offset1:164
	ds_write2_b32 v141, v22, v23 offset0:40 offset1:172
	ds_write2_b32 v142, v24, v25 offset0:64 offset1:196
	ds_write2_b32 v143, v26, v27 offset0:72 offset1:204
	ds_write2_b32 v144, v28, v29 offset0:96 offset1:228
	ds_write2_b32 v145, v30, v31 offset0:104 offset1:236
	s_waitcnt lgkmcnt(9)
	v_mfma_f32_32x32x16_bf16 v[0:15], v[40:43], v[36:39], v[0:15]
	s_waitcnt lgkmcnt(8)
	v_mfma_f32_32x32x16_bf16 v[0:15], v[44:47], v[32:35], v[0:15]
	s_nop 11
	ds_write2_b32 v146, v0, v1 offset1:132
	ds_write2_b32 v147, v2, v3 offset0:8 offset1:140
	ds_write2_b32 v148, v4, v5 offset0:32 offset1:164
	ds_write2_b32 v149, v6, v7 offset0:40 offset1:172
	ds_write2_b32 v150, v8, v9 offset0:64 offset1:196
	ds_write2_b32 v151, v10, v11 offset0:72 offset1:204
	ds_write2_b32 v152, v12, v13 offset0:96 offset1:228
	ds_write2_b32 v153, v14, v15 offset0:104 offset1:236
	s_waitcnt lgkmcnt(0)
	s_barrier
; __device__ __forceinline__ unsigned pk2(float a, float b) { f32v2 v = {a, b}; bf16v2 r = __builtin_convertvector(v, bf16v2); return __builtin_bit_cast(unsigned, r); }
; __device__ __forceinline__ float silu_(float x) { return x * sigmoid_(x); }
; __device__ __forceinline__ size_t a_off(int row, int col, int nks) { return ((size_t)((row >> 8) * nks + (col >> 5)) << 13) + ((row & 255) << 5) + swzc(row, col & 31); }
; __device__ __forceinline__ void gdn_out_phase(const Params& p, char* smem, int bid, int nblk) {
;     ...
;       const int tok = tid >> 2, part = tid & 3;
;       const int row = b * SEQ + n * 64 + tok;
;       f32x4 a[8]; float ss = 0.f;
; #pragma unroll
;       for (int k = 0; k < 8; ++k) { a[k] = *(const f32x4*)(Ol + tok * 132 + part * 32 + k * 4); ss += a[k][0] * a[k][0] + a[k][1] * a[k][1] + a[k][2] * a[k][2] + a[k][3] * a[k][3]; }
;       ss += __shfl_xor(ss, 1); ss += __shfl_xor(ss, 2);
;       const float rs = rsqrtf(ss * (1.f / 128.f) + 1e-6f);
;       const u16* zp = zb + (size_t)row * 512 + h * 128 + part * 32;
;       const float* hw = p.hy_head_norm_w + part * 32;
;       const int ccol = h * 128 + part * 32;
; #pragma unroll
;       for (int k = 0; k < 4; ++k) {
;         float zf[8]; unpack8(*(const u32x4*)(zp + k * 8), zf);
;         const f32x4 h0 = *(const f32x4*)(hw + k * 8), h1 = *(const f32x4*)(hw + k * 8 + 4);
;         const f32x4 x0 = a[2 * k], x1 = a[2 * k + 1];
;         u32x4 w;
;         w[0] = pk2(x0[0] * rs * h0[0] * silu_(zf[0]), x0[1] * rs * h0[1] * silu_(zf[1]));
;         w[1] = pk2(x0[2] * rs * h0[2] * silu_(zf[2]), x0[3] * rs * h0[3] * silu_(zf[3]));
;         w[2] = pk2(x1[0] * rs * h1[0] * silu_(zf[4]), x1[1] * rs * h1[1] * silu_(zf[5]));
;         w[3] = pk2(x1[2] * rs * h1[2] * silu_(zf[6]), x1[3] * rs * h1[3] * silu_(zf[7]));
;         *(u32x4*)(concat + a_off(row, ccol + k * 8, 32)) = w;
	ds_read_b128 v[10:13], v133 offset:25600
	ds_read_b128 v[14:17], v133 offset:25616
	ds_read_b128 v[18:21], v133 offset:25632
	ds_read_b128 v[22:25], v133 offset:25648
	ds_read_b128 v[26:29], v133 offset:25664
	ds_read_b128 v[30:33], v133 offset:25680
	ds_read_b128 v[4:7], v133 offset:25696
	ds_read_b128 v[0:3], v133 offset:25712
	global_load_dwordx4 v[34:37], v[114:115], off
	global_load_dwordx4 v[38:41], v[86:87], off offset:16
	global_load_dwordx4 v[42:45], v[86:87], off
	s_waitcnt lgkmcnt(7)
	v_mov_b32_e32 v46, v11
	s_waitcnt lgkmcnt(6)
	v_mov_b32_e32 v47, v15
	v_mov_b32_e32 v8, v10
	v_mov_b32_e32 v9, v14
	s_waitcnt lgkmcnt(5)
	v_mov_b32_e32 v54, v19
	s_waitcnt lgkmcnt(4)
	v_mov_b32_e32 v55, v23
	v_pk_mul_f32 v[46:47], v[46:47], v[46:47]
	v_mov_b32_e32 v48, v12
	v_mov_b32_e32 v49, v16
	v_mov_b32_e32 v52, v18
	v_mov_b32_e32 v53, v22
	v_pk_mul_f32 v[54:55], v[54:55], v[54:55]
	v_pk_fma_f32 v[8:9], v[8:9], v[8:9], v[46:47]
	v_mov_b32_e32 v50, v13
	v_mov_b32_e32 v51, v17
	v_mov_b32_e32 v56, v20
	v_mov_b32_e32 v57, v24
	s_waitcnt lgkmcnt(3)
	v_mov_b32_e32 v62, v27
	s_waitcnt lgkmcnt(2)
	v_mov_b32_e32 v63, v31
	v_pk_fma_f32 v[46:47], v[52:53], v[52:53], v[54:55]
	v_pk_fma_f32 v[8:9], v[48:49], v[48:49], v[8:9]
	v_mov_b32_e32 v58, v21
	v_mov_b32_e32 v59, v25
	v_mov_b32_e32 v60, v26
	v_mov_b32_e32 v61, v30
	v_pk_mul_f32 v[62:63], v[62:63], v[62:63]
	v_pk_fma_f32 v[46:47], v[56:57], v[56:57], v[46:47]
	v_pk_fma_f32 v[8:9], v[50:51], v[50:51], v[8:9]
	v_mov_b32_e32 v64, v28
	v_mov_b32_e32 v65, v32
	s_waitcnt lgkmcnt(1)
	v_mov_b32_e32 v70, v5
	s_waitcnt lgkmcnt(0)
	v_mov_b32_e32 v71, v1
	v_pk_fma_f32 v[52:53], v[60:61], v[60:61], v[62:63]
	v_pk_fma_f32 v[46:47], v[58:59], v[58:59], v[46:47]
	v_add_f32_e32 v8, v8, v9
	v_mov_b32_e32 v66, v29
	v_mov_b32_e32 v67, v33
	v_mov_b32_e32 v68, v4
	v_mov_b32_e32 v69, v0
	v_pk_mul_f32 v[70:71], v[70:71], v[70:71]
	v_pk_fma_f32 v[48:49], v[64:65], v[64:65], v[52:53]
	v_add_f32_e32 v8, v8, v46
	v_mov_b32_e32 v72, v6
	v_mov_b32_e32 v73, v2
	v_pk_fma_f32 v[54:55], v[68:69], v[68:69], v[70:71]
	v_pk_fma_f32 v[48:49], v[66:67], v[66:67], v[48:49]
	v_add_f32_e32 v8, v8, v47
	v_mov_b32_e32 v74, v7
	v_mov_b32_e32 v75, v3
	v_pk_fma_f32 v[52:53], v[72:73], v[72:73], v[54:55]
	v_add_f32_e32 v8, v8, v48
	v_pk_fma_f32 v[50:51], v[74:75], v[74:75], v[52:53]
	v_add_f32_e32 v8, v8, v49
	v_add_f32_e32 v8, v8, v50
	v_add_f32_e32 v8, v8, v51
	ds_bpermute_b32 v9, v124, v8
	s_waitcnt lgkmcnt(0)
	v_add_f32_e32 v8, v8, v9
	ds_bpermute_b32 v9, v125, v8
	s_waitcnt lgkmcnt(0)
	v_add_f32_e32 v8, v8, v9
	v_fmamk_f32 v8, v8, 0x3c000000, v134
	v_mul_f32_e32 v9, 0x4b800000, v8
	v_cmp_gt_f32_e32 vcc, s14, v8
	s_nop 1
	v_cndmask_b32_e32 v8, v8, v9, vcc
	v_rsq_f32_e32 v8, v8
	s_nop 0
	v_mul_f32_e32 v9, 0x45800000, v8
	v_cndmask_b32_e32 v8, v8, v9, vcc
	v_pk_mul_f32 v[10:11], v[10:11], v[8:9] op_sel_hi:[1,0]
	v_pk_mul_f32 v[12:13], v[12:13], v[8:9] op_sel_hi:[1,0]
	v_pk_mul_f32 v[14:15], v[14:15], v[8:9] op_sel_hi:[1,0]
	v_pk_mul_f32 v[16:17], v[16:17], v[8:9] op_sel_hi:[1,0]
	v_pk_mul_f32 v[46:47], v[18:19], v[8:9] op_sel_hi:[1,0]
	v_pk_mul_f32 v[48:49], v[20:21], v[8:9] op_sel_hi:[1,0]
	s_waitcnt vmcnt(2)
	v_lshlrev_b32_e32 v18, 16, v34
	v_and_b32_e32 v19, 0xffff0000, v34
	v_lshlrev_b32_e32 v20, 16, v35
	v_and_b32_e32 v21, 0xffff0000, v35
	v_lshlrev_b32_e32 v34, 16, v36
	v_and_b32_e32 v35, 0xffff0000, v36
	v_lshlrev_b32_e32 v36, 16, v37
	v_and_b32_e32 v37, 0xffff0000, v37
	v_pk_mul_f32 v[22:23], v[22:23], v[8:9] op_sel_hi:[1,0]
	v_pk_mul_f32 v[24:25], v[24:25], v[8:9] op_sel_hi:[1,0]
	v_pk_mul_f32 v[26:27], v[26:27], v[8:9] op_sel_hi:[1,0]
	v_pk_mul_f32 v[28:29], v[28:29], v[8:9] op_sel_hi:[1,0]
	v_pk_mul_f32 v[30:31], v[30:31], v[8:9] op_sel_hi:[1,0]
	v_pk_mul_f32 v[32:33], v[32:33], v[8:9] op_sel_hi:[1,0]
	s_waitcnt vmcnt(0)
	v_pk_mul_f32 v[10:11], v[42:43], v[10:11]
	v_pk_mul_f32 v[12:13], v[44:45], v[12:13]
	v_pk_mul_f32 v[14:15], v[38:39], v[14:15]
	v_pk_mul_f32 v[16:17], v[40:41], v[16:17]
	v_mul_f32_e32 v9, 0xbfb8aa3b, v18
	v_mul_f32_e32 v38, 0xbfb8aa3b, v19
	v_mul_f32_e32 v39, 0xbfb8aa3b, v20
	v_mul_f32_e32 v40, 0xbfb8aa3b, v21
	v_mul_f32_e32 v41, 0xbfb8aa3b, v34
	v_mul_f32_e32 v42, 0xbfb8aa3b, v35
	v_mul_f32_e32 v43, 0xbfb8aa3b, v36
	v_mul_f32_e32 v44, 0xbfb8aa3b, v37
	v_exp_f32_e32 v9, v9
	v_exp_f32_e32 v38, v38
	v_exp_f32_e32 v39, v39
	v_exp_f32_e32 v40, v40
	v_exp_f32_e32 v41, v41
	v_exp_f32_e32 v42, v42
	v_exp_f32_e32 v43, v43
	v_exp_f32_e32 v44, v44
	v_add_f32_e32 v9, 1.0, v9
	v_add_f32_e32 v45, 1.0, v38
	v_add_f32_e32 v50, 1.0, v39
	v_add_f32_e32 v51, 1.0, v40
	v_add_f32_e32 v52, 1.0, v41
	v_add_f32_e32 v53, 1.0, v42
	v_add_f32_e32 v54, 1.0, v43
	v_add_f32_e32 v55, 1.0, v44
	v_rcp_f32_e32 v38, v9
	v_rcp_f32_e32 v39, v45
	v_rcp_f32_e32 v40, v50
	v_rcp_f32_e32 v41, v51
	v_rcp_f32_e32 v42, v52
	v_rcp_f32_e32 v43, v53
	v_rcp_f32_e32 v44, v54
	v_rcp_f32_e32 v45, v55
	v_pk_mul_f32 v[18:19], v[38:39], v[18:19]
	v_pk_mul_f32 v[20:21], v[40:41], v[20:21]
	v_pk_mul_f32 v[34:35], v[42:43], v[34:35]
	v_pk_mul_f32 v[36:37], v[44:45], v[36:37]
	v_pk_mul_f32 v[10:11], v[18:19], v[10:11]
	v_pk_mul_f32 v[12:13], v[20:21], v[12:13]
	v_pk_mul_f32 v[14:15], v[34:35], v[14:15]
	v_pk_mul_f32 v[16:17], v[36:37], v[16:17]
	v_cvt_pk_bf16_f32 v10, v10, v11
	v_cvt_pk_bf16_f32 v11, v12, v13
	v_cvt_pk_bf16_f32 v12, v14, v15
	v_cvt_pk_bf16_f32 v13, v16, v17
	v_mov_b32_e32 v250, v116
	v_mov_b32_e32 v251, v117
	v_mov_b32_e32 v252, v10
	v_mov_b32_e32 v253, v11
	v_mov_b32_e32 v254, v12
	v_mov_b32_e32 v255, v13
	global_load_dwordx4 v[10:13], v[114:115], off offset:16
	s_nop 0
	global_load_dwordx4 v[14:17], v[86:87], off offset:32
	global_load_dwordx4 v[18:21], v[86:87], off offset:48
	global_store_dwordx4 v[250:251], v[252:255], off
	s_nop 1
	s_waitcnt vmcnt(3)
; __device__ __forceinline__ unsigned pk2(float a, float b) { f32v2 v = {a, b}; bf16v2 r = __builtin_convertvector(v, bf16v2); return __builtin_bit_cast(unsigned, r); }
; __device__ __forceinline__ float silu_(float x) { return x * sigmoid_(x); }
; __device__ __forceinline__ size_t a_off(int row, int col, int nks) { return ((size_t)((row >> 8) * nks + (col >> 5)) << 13) + ((row & 255) << 5) + swzc(row, col & 31); }
; __device__ __forceinline__ void gdn_out_phase(const Params& p, char* smem, int bid, int nblk) {
;     ...
;       for (int k = 0; k < 4; ++k) {
;         float zf[8]; unpack8(*(const u32x4*)(zp + k * 8), zf);
;         const f32x4 h0 = *(const f32x4*)(hw + k * 8), h1 = *(const f32x4*)(hw + k * 8 + 4);
;         const f32x4 x0 = a[2 * k], x1 = a[2 * k + 1];
;         u32x4 w;
;         w[0] = pk2(x0[0] * rs * h0[0] * silu_(zf[0]), x0[1] * rs * h0[1] * silu_(zf[1]));
;         w[1] = pk2(x0[2] * rs * h0[2] * silu_(zf[2]), x0[3] * rs * h0[3] * silu_(zf[3]));
;         w[2] = pk2(x1[0] * rs * h1[0] * silu_(zf[4]), x1[1] * rs * h1[1] * silu_(zf[5]));
;         w[3] = pk2(x1[2] * rs * h1[2] * silu_(zf[6]), x1[3] * rs * h1[3] * silu_(zf[7]));
;         *(u32x4*)(concat + a_off(row, ccol + k * 8, 32)) = w;
;       }
;     }
;     __syncthreads();
	v_lshlrev_b32_e32 v34, 16, v10
	v_and_b32_e32 v35, 0xffff0000, v10
	v_lshlrev_b32_e32 v10, 16, v11
	v_and_b32_e32 v11, 0xffff0000, v11
	v_lshlrev_b32_e32 v36, 16, v12
	v_and_b32_e32 v37, 0xffff0000, v12
	v_lshlrev_b32_e32 v12, 16, v13
	v_and_b32_e32 v13, 0xffff0000, v13
	s_waitcnt vmcnt(1)
	v_pk_mul_f32 v[18:19], v[18:19], v[22:23]
	v_pk_mul_f32 v[20:21], v[20:21], v[24:25]
	v_mul_f32_e32 v9, 0xbfb8aa3b, v34
	v_mul_f32_e32 v22, 0xbfb8aa3b, v35
	v_mul_f32_e32 v23, 0xbfb8aa3b, v10
	v_mul_f32_e32 v24, 0xbfb8aa3b, v11
	v_mul_f32_e32 v25, 0xbfb8aa3b, v36
	v_mul_f32_e32 v38, 0xbfb8aa3b, v37
	v_mul_f32_e32 v39, 0xbfb8aa3b, v12
	v_mul_f32_e32 v40, 0xbfb8aa3b, v13
	v_exp_f32_e32 v9, v9
	v_exp_f32_e32 v22, v22
	v_exp_f32_e32 v23, v23
	v_exp_f32_e32 v24, v24
	v_exp_f32_e32 v25, v25
	v_exp_f32_e32 v38, v38
	v_exp_f32_e32 v39, v39
	v_exp_f32_e32 v40, v40
	v_pk_mul_f32 v[14:15], v[14:15], v[46:47]
	v_add_f32_e32 v9, 1.0, v9
	v_add_f32_e32 v41, 1.0, v22
	v_add_f32_e32 v42, 1.0, v23
	v_add_f32_e32 v43, 1.0, v24
	v_add_f32_e32 v44, 1.0, v25
	v_add_f32_e32 v45, 1.0, v38
	v_add_f32_e32 v46, 1.0, v39
	v_add_f32_e32 v47, 1.0, v40
	v_rcp_f32_e32 v22, v9
	v_rcp_f32_e32 v23, v41
	v_rcp_f32_e32 v24, v42
	v_rcp_f32_e32 v25, v43
	v_rcp_f32_e32 v38, v44
	v_rcp_f32_e32 v39, v45
	v_rcp_f32_e32 v40, v46
	v_rcp_f32_e32 v41, v47
	v_pk_mul_f32 v[16:17], v[16:17], v[48:49]
	v_pk_mul_f32 v[22:23], v[22:23], v[34:35]
	v_pk_mul_f32 v[10:11], v[24:25], v[10:11]
	v_pk_mul_f32 v[24:25], v[38:39], v[36:37]
	v_pk_mul_f32 v[12:13], v[40:41], v[12:13]
	v_pk_mul_f32 v[14:15], v[22:23], v[14:15]
	v_pk_mul_f32 v[16:17], v[10:11], v[16:17]
	v_pk_mul_f32 v[18:19], v[24:25], v[18:19]
	v_pk_mul_f32 v[20:21], v[12:13], v[20:21]
	v_cvt_pk_bf16_f32 v10, v14, v15
	v_cvt_pk_bf16_f32 v11, v16, v17
	v_cvt_pk_bf16_f32 v12, v18, v19
	v_cvt_pk_bf16_f32 v13, v20, v21
	v_mov_b32_e32 v250, v118
	v_mov_b32_e32 v251, v119
	v_mov_b32_e32 v252, v10
	v_mov_b32_e32 v253, v11
	v_mov_b32_e32 v254, v12
	v_mov_b32_e32 v255, v13
	global_load_dwordx4 v[10:13], v[114:115], off offset:32
	s_nop 0
	global_load_dwordx4 v[14:17], v[86:87], off offset:64
	global_load_dwordx4 v[18:21], v[86:87], off offset:80
	global_store_dwordx4 v[250:251], v[252:255], off
	s_nop 1
	s_waitcnt vmcnt(3)
	v_lshlrev_b32_e32 v22, 16, v10
	v_and_b32_e32 v23, 0xffff0000, v10
	v_lshlrev_b32_e32 v10, 16, v11
	v_and_b32_e32 v11, 0xffff0000, v11
	v_lshlrev_b32_e32 v24, 16, v12
	v_and_b32_e32 v25, 0xffff0000, v12
	v_lshlrev_b32_e32 v12, 16, v13
	v_and_b32_e32 v13, 0xffff0000, v13
	s_waitcnt vmcnt(2)
	v_pk_mul_f32 v[14:15], v[14:15], v[26:27]
	v_pk_mul_f32 v[16:17], v[16:17], v[28:29]
	s_waitcnt vmcnt(1)
	v_pk_mul_f32 v[18:19], v[18:19], v[30:31]
	v_pk_mul_f32 v[20:21], v[20:21], v[32:33]
	v_mul_f32_e32 v9, 0xbfb8aa3b, v22
	v_mul_f32_e32 v26, 0xbfb8aa3b, v23
	v_mul_f32_e32 v27, 0xbfb8aa3b, v10
	v_mul_f32_e32 v28, 0xbfb8aa3b, v11
	v_mul_f32_e32 v29, 0xbfb8aa3b, v24
	v_mul_f32_e32 v30, 0xbfb8aa3b, v25
	v_mul_f32_e32 v31, 0xbfb8aa3b, v12
	v_mul_f32_e32 v32, 0xbfb8aa3b, v13
	v_exp_f32_e32 v9, v9
	v_exp_f32_e32 v26, v26
	v_exp_f32_e32 v27, v27
	v_exp_f32_e32 v28, v28
	v_exp_f32_e32 v29, v29
	v_exp_f32_e32 v30, v30
	v_exp_f32_e32 v31, v31
	v_exp_f32_e32 v32, v32
	v_add_f32_e32 v9, 1.0, v9
	v_add_f32_e32 v33, 1.0, v26
	v_add_f32_e32 v34, 1.0, v27
	v_add_f32_e32 v35, 1.0, v28
	v_add_f32_e32 v36, 1.0, v29
	v_add_f32_e32 v37, 1.0, v30
	v_add_f32_e32 v38, 1.0, v31
	v_add_f32_e32 v39, 1.0, v32
	v_rcp_f32_e32 v26, v9
	v_rcp_f32_e32 v27, v33
	v_rcp_f32_e32 v28, v34
	v_rcp_f32_e32 v29, v35
	v_rcp_f32_e32 v30, v36
	v_rcp_f32_e32 v31, v37
	v_rcp_f32_e32 v32, v38
	v_rcp_f32_e32 v33, v39
	v_pk_mul_f32 v[22:23], v[26:27], v[22:23]
	v_pk_mul_f32 v[10:11], v[28:29], v[10:11]
	v_pk_mul_f32 v[24:25], v[30:31], v[24:25]
	v_pk_mul_f32 v[12:13], v[32:33], v[12:13]
	v_pk_mul_f32 v[14:15], v[14:15], v[22:23]
	v_pk_mul_f32 v[16:17], v[16:17], v[10:11]
	v_pk_mul_f32 v[18:19], v[18:19], v[24:25]
	v_pk_mul_f32 v[20:21], v[20:21], v[12:13]
	v_cvt_pk_bf16_f32 v10, v14, v15
	v_cvt_pk_bf16_f32 v11, v16, v17
	v_cvt_pk_bf16_f32 v12, v18, v19
	v_cvt_pk_bf16_f32 v13, v20, v21
	v_mov_b32_e32 v250, v120
	v_mov_b32_e32 v251, v121
	v_mov_b32_e32 v252, v10
	v_mov_b32_e32 v253, v11
	v_mov_b32_e32 v254, v12
	v_mov_b32_e32 v255, v13
	global_load_dwordx4 v[10:13], v[114:115], off offset:48
	s_nop 0
	global_load_dwordx4 v[14:17], v[86:87], off offset:96
	global_load_dwordx4 v[18:21], v[86:87], off offset:112
	global_store_dwordx4 v[250:251], v[252:255], off
	s_nop 1
	v_pk_mul_f32 v[4:5], v[4:5], v[8:9] op_sel_hi:[1,0]
	v_pk_mul_f32 v[6:7], v[6:7], v[8:9] op_sel_hi:[1,0]
	v_pk_mul_f32 v[0:1], v[0:1], v[8:9] op_sel_hi:[1,0]
	v_pk_mul_f32 v[2:3], v[2:3], v[8:9] op_sel_hi:[1,0]
	v_lshl_add_u64 v[22:23], v[112:113], 0, v[110:111]
	s_waitcnt vmcnt(3)
	v_lshlrev_b32_e32 v8, 16, v10
	v_and_b32_e32 v9, 0xffff0000, v10
	s_waitcnt vmcnt(2)
	v_pk_mul_f32 v[4:5], v[14:15], v[4:5]
	v_lshlrev_b32_e32 v10, 16, v11
	v_and_b32_e32 v11, 0xffff0000, v11
	v_lshlrev_b32_e32 v14, 16, v12
	v_and_b32_e32 v15, 0xffff0000, v12
	v_lshlrev_b32_e32 v12, 16, v13
	v_and_b32_e32 v13, 0xffff0000, v13
	v_pk_mul_f32 v[6:7], v[16:17], v[6:7]
	s_waitcnt vmcnt(1)
	v_pk_mul_f32 v[0:1], v[0:1], v[18:19]
	v_pk_mul_f32 v[2:3], v[2:3], v[20:21]
	v_mul_f32_e32 v16, 0xbfb8aa3b, v8
	v_mul_f32_e32 v17, 0xbfb8aa3b, v9
	v_mul_f32_e32 v18, 0xbfb8aa3b, v10
	v_mul_f32_e32 v19, 0xbfb8aa3b, v11
	v_mul_f32_e32 v20, 0xbfb8aa3b, v14
	v_mul_f32_e32 v21, 0xbfb8aa3b, v15
	v_mul_f32_e32 v24, 0xbfb8aa3b, v12
	v_mul_f32_e32 v25, 0xbfb8aa3b, v13
	v_exp_f32_e32 v16, v16
	v_exp_f32_e32 v17, v17
	v_exp_f32_e32 v18, v18
	v_exp_f32_e32 v19, v19
	v_exp_f32_e32 v20, v20
	v_exp_f32_e32 v21, v21
	v_exp_f32_e32 v24, v24
	v_exp_f32_e32 v25, v25
	v_add_f32_e32 v16, 1.0, v16
	v_add_f32_e32 v17, 1.0, v17
	v_add_f32_e32 v18, 1.0, v18
	v_add_f32_e32 v19, 1.0, v19
	v_add_f32_e32 v20, 1.0, v20
	v_add_f32_e32 v21, 1.0, v21
	v_add_f32_e32 v24, 1.0, v24
	v_add_f32_e32 v25, 1.0, v25
	v_rcp_f32_e32 v16, v16
	v_rcp_f32_e32 v17, v17
	v_rcp_f32_e32 v18, v18
	v_rcp_f32_e32 v19, v19
	v_rcp_f32_e32 v20, v20
	v_rcp_f32_e32 v21, v21
	v_rcp_f32_e32 v24, v24
	v_rcp_f32_e32 v25, v25
	v_pk_mul_f32 v[8:9], v[16:17], v[8:9]
	v_pk_mul_f32 v[10:11], v[18:19], v[10:11]
	v_pk_mul_f32 v[14:15], v[20:21], v[14:15]
	v_pk_mul_f32 v[12:13], v[24:25], v[12:13]
	v_pk_mul_f32 v[4:5], v[4:5], v[8:9]
	v_pk_mul_f32 v[6:7], v[6:7], v[10:11]
	v_pk_mul_f32 v[8:9], v[0:1], v[14:15]
	v_pk_mul_f32 v[10:11], v[2:3], v[12:13]
	v_cvt_pk_bf16_f32 v0, v4, v5
	v_cvt_pk_bf16_f32 v1, v6, v7
	v_cvt_pk_bf16_f32 v2, v8, v9
	v_cvt_pk_bf16_f32 v3, v10, v11
	global_store_dwordx4 v[22:23], v[0:3], off
	s_barrier
	s_cbranch_scc1 .LBB0_1266

; __device__ __forceinline__ unsigned pk2(float a, float b) { f32v2 v = {a, b}; bf16v2 r = __builtin_convertvector(v, bf16v2); return __builtin_bit_cast(unsigned, r); }
; __device__ __forceinline__ float sigmoid_(float x) { return __builtin_amdgcn_rcpf(1.f + __expf(-x)); }
; __device__ __forceinline__ size_t pj_idx(int row, int col) { return (size_t)(col >> 9) * ((size_t)M * 512) + (size_t)row * 512 + (col & 511); }
; __device__ __forceinline__ size_t a_off(int row, int col, int nks) { return ((size_t)((row >> 8) * nks + (col >> 5)) << 13) + ((row & 255) << 5) + swzc(row, col & 31); }
; template <int EPI>
; __device__ __forceinline__ void gemm_phase(const u16* __restrict__ A0, int nksA, size_t sA, const u16* __restrict__ B0, int nksB, size_t sB,
;                                            int K, int nM, int nN, int nbatch, const EpiArgs ea, char* smem, int bid, int nblk) {
;     ...
;         const int row = brow + wr * 128 + m * 16 + fr, col = bcol + wc * 64 + n * 16 + fq * 4;
;         const f32x4 v = acc[m][n];
;         if (EPI == E_PROJ0) {
;           const uint2 pk = uint2{pk2(v[0], v[1]), pk2(v[2], v[3])};
;           if (bcol < 2048) *(uint2*)(ea.outb + pj_idx(row, col)) = pk;
;           else { const int cc = col - 2048; *(uint2*)(ea.ux + (size_t)(cc >> 4) * S5C * UXW + a_off(row >> 5, (row & 31) * 16 + (cc & 15), 20)) = pk; }
;         }
;         if (EPI == E_BF16) *(uint2*)(ea.outb + (size_t)row * ea.ldc + col) = uint2{pk2(v[0], v[1]), pk2(v[2], v[3])};
;         if (EPI == E_RESID) {
;           const size_t idx = (size_t)row * 1024 + col;
;           const f32x4 r4 = *(const f32x4*)(ea.res + idx), g4 = *(const f32x4*)(ea.gate + (size_t)(row >> 13) * 6144 + col);
;           *(f32x4*)(ea.outf + idx) = f32x4{r4[0] + g4[0] * v[0], r4[1] + g4[1] * v[1], r4[2] + g4[2] * v[2], r4[3] + g4[3] * v[3]};
;         }
;         if (EPI == E_GLU) {
;           const uint2 yy = *(const uint2*)(ea.y5 + a_off(row, col, 16));
;           const f32x4 b4 = *(const f32x4*)(ea.bias + col);
;           const float y0 = __uint_as_float(yy.x << 16), y1 = __uint_as_float(yy.x & 0xffff0000u), y2 = __uint_as_float(yy.y << 16), y3 = __uint_as_float(yy.y & 0xffff0000u);
;           *(uint2*)(ea.outb + a_off(row, 512 + col, 32)) = uint2{pk2(y0 * sigmoid_(v[0] + b4[0]), y1 * sigmoid_(v[1] + b4[1])), pk2(y2 * sigmoid_(v[2] + b4[2]), y3 * sigmoid_(v[3] + b4[3]))};
.LBB0_1268:
	v_lshl_or_b32 v178, s48, 7, v180
	v_or_b32_e32 v154, v178, v134
	v_ashrrev_i32_e32 v155, 31, v154
	v_lshl_add_u32 v147, s42, 8, v181
	v_lshl_add_u64 v[154:155], v[154:155], 2, s[20:21]
	v_ashrrev_i32_e32 v147, 8, v147
	global_load_dwordx4 v[170:173], v[154:155], off
	v_ashrrev_i32_e32 v149, 5, v178
	v_lshlrev_b32_e32 v151, 4, v147
	v_add_u32_e32 v156, v151, v149
	v_ashrrev_i32_e32 v157, 31, v156
	v_lshlrev_b64 v[156:157], 14, v[156:157]
	v_lshl_add_u64 v[160:161], v[138:139], 0, v[156:157]
	v_lshl_add_u64 v[164:165], v[160:161], 0, v[136:137]
	global_load_dwordx2 v[162:163], v[164:165], off
	v_add_u32_e32 v149, 0x200, v178
	v_lshlrev_b32_e32 v147, 5, v147
	v_ashrrev_i32_e32 v149, 5, v149
	v_add_u32_e32 v158, v147, v149
	v_ashrrev_i32_e32 v159, 31, v158
	v_lshlrev_b64 v[158:159], 14, v[158:159]
	v_ashrrev_i32_e32 v179, 31, v178
	v_lshl_add_u64 v[158:159], v[140:141], 0, v[158:159]
	v_lshl_add_u64 v[174:175], v[178:179], 0, v[134:135]
	v_lshl_add_u64 v[166:167], v[158:159], 0, v[136:137]
	v_lshl_add_u64 v[156:157], v[142:143], 0, v[156:157]
	v_lshl_add_u64 v[168:169], v[156:157], 0, v[136:137]
	v_mov_b32_e32 v207, v137
	s_waitcnt vmcnt(0)
	v_add_f32_e32 v124, v124, v170
	v_add_f32_e32 v125, v125, v171
	v_add_f32_e32 v126, v126, v172
	v_add_f32_e32 v127, v127, v173
	v_mul_f32_e32 v124, 0xbfb8aa3b, v124
	v_mul_f32_e32 v125, 0xbfb8aa3b, v125
	v_mul_f32_e32 v126, 0xbfb8aa3b, v126
	v_mul_f32_e32 v127, 0xbfb8aa3b, v127
	v_exp_f32_e32 v149, v124
	v_exp_f32_e32 v153, v125
	v_exp_f32_e32 v126, v126
	v_exp_f32_e32 v127, v127
	v_lshlrev_b32_e32 v124, 16, v162
	v_and_b32_e32 v125, 0xffff0000, v162
	v_add_f32_e32 v149, 1.0, v149
	v_add_f32_e32 v153, 1.0, v153
	v_add_f32_e32 v162, 1.0, v126
	v_add_f32_e32 v171, 1.0, v127
	v_rcp_f32_e32 v126, v149
	v_rcp_f32_e32 v127, v153
	v_rcp_f32_e32 v170, v162
	v_rcp_f32_e32 v171, v171
	v_lshlrev_b32_e32 v162, 16, v163
	v_and_b32_e32 v163, 0xffff0000, v163
	v_pk_mul_f32 v[124:125], v[126:127], v[124:125]
	v_pk_mul_f32 v[126:127], v[170:171], v[162:163]
	v_cvt_pk_bf16_f32 v124, v124, v125
	v_cvt_pk_bf16_f32 v125, v126, v127
	v_mov_b32_e32 v250, v166
	v_mov_b32_e32 v251, v167
	v_mov_b32_e32 v252, v124
	v_mov_b32_e32 v253, v125
	v_lshl_add_u64 v[124:125], v[174:175], 2, s[20:21]
	global_load_dwordx4 v[174:177], v[124:125], off offset:64
	global_load_dwordx2 v[200:201], v[168:169], off
	global_store_dwordx2 v[250:251], v[252:253], off
	v_add_u32_e32 v126, 0x210, v178
	v_or_b32_e32 v127, 32, v178
	v_ashrrev_i32_e32 v126, 5, v126
	v_ashrrev_i32_e32 v127, 5, v127
	v_add_u32_e32 v126, v147, v126
	v_add_u32_e32 v162, v151, v127
	v_ashrrev_i32_e32 v127, 31, v126
	v_ashrrev_i32_e32 v163, 31, v162
	v_lshlrev_b64 v[126:127], 14, v[126:127]
	v_lshlrev_b64 v[170:171], 14, v[162:163]
	v_lshl_add_u64 v[162:163], v[144:145], 0, v[126:127]
	v_lshl_add_u64 v[126:127], v[138:139], 0, v[170:171]
	v_lshl_add_u64 v[170:171], v[162:163], 0, v[136:137]
	v_lshl_add_u64 v[172:173], v[126:127], 0, v[136:137]
	v_mov_b32_e32 v153, v137
	s_waitcnt vmcnt(1)
	v_add_f32_e32 v120, v120, v174
	v_add_f32_e32 v121, v121, v175
	v_add_f32_e32 v122, v122, v176
	v_add_f32_e32 v123, v123, v177
	v_mul_f32_e32 v120, 0xbfb8aa3b, v120
	v_mul_f32_e32 v121, 0xbfb8aa3b, v121
	v_mul_f32_e32 v122, 0xbfb8aa3b, v122
	v_mul_f32_e32 v123, 0xbfb8aa3b, v123
	v_exp_f32_e32 v120, v120
	v_exp_f32_e32 v121, v121
	v_exp_f32_e32 v122, v122
	v_exp_f32_e32 v123, v123
	v_add_f32_e32 v120, 1.0, v120
	v_add_f32_e32 v121, 1.0, v121
	v_add_f32_e32 v122, 1.0, v122
	v_add_f32_e32 v123, 1.0, v123
	v_rcp_f32_e32 v120, v120
	v_rcp_f32_e32 v121, v121
	v_rcp_f32_e32 v122, v122
	v_rcp_f32_e32 v123, v123
	v_lshlrev_b32_e32 v202, 16, v200
	v_and_b32_e32 v203, 0xffff0000, v200
	v_lshlrev_b32_e32 v174, 16, v201
	v_and_b32_e32 v175, 0xffff0000, v201
	v_pk_mul_f32 v[120:121], v[120:121], v[202:203]
	v_pk_mul_f32 v[122:123], v[122:123], v[174:175]
	v_cvt_pk_bf16_f32 v120, v120, v121
	v_cvt_pk_bf16_f32 v121, v122, v123
	v_mov_b32_e32 v250, v170
	v_mov_b32_e32 v251, v171
	v_mov_b32_e32 v252, v120
	v_mov_b32_e32 v253, v121
	global_load_dwordx2 v[204:205], v[172:173], off
	global_load_dwordx4 v[200:203], v[124:125], off offset:128
	global_store_dwordx2 v[250:251], v[252:253], off
	v_add_u32_e32 v120, 0x220, v178
	v_or_b32_e32 v121, 48, v178
	v_ashrrev_i32_e32 v120, 5, v120
	v_ashrrev_i32_e32 v122, 5, v121
	v_bitop3_b32 v121, v121, v184, v134 bitop3:0x36
	v_add_u32_e32 v120, v147, v120
	v_add_u32_e32 v122, v151, v122
	v_and_or_b32 v149, v121, 24, v185
	v_ashrrev_i32_e32 v121, 31, v120
	v_ashrrev_i32_e32 v123, 31, v122
	v_lshlrev_b64 v[120:121], 14, v[120:121]
	v_lshlrev_b64 v[174:175], 14, v[122:123]
	v_lshlrev_b32_e32 v206, 1, v149
	v_lshl_add_u64 v[122:123], v[140:141], 0, v[120:121]
	v_lshl_add_u64 v[120:121], s[0:1], 0, v[174:175]
	v_lshl_add_u64 v[174:175], v[122:123], 0, v[136:137]
	v_lshl_add_u64 v[120:121], v[120:121], 0, v[206:207]
	v_lshl_add_u64 v[176:177], v[120:121], 0, v[136:137]
	v_mov_b32_e32 v149, v137
	v_mov_b32_e32 v151, v137
	s_waitcnt vmcnt(1)
; __device__ __forceinline__ unsigned pk2(float a, float b) { f32v2 v = {a, b}; bf16v2 r = __builtin_convertvector(v, bf16v2); return __builtin_bit_cast(unsigned, r); }
; __device__ __forceinline__ float sigmoid_(float x) { return __builtin_amdgcn_rcpf(1.f + __expf(-x)); }
; __device__ __forceinline__ size_t pj_idx(int row, int col) { return (size_t)(col >> 9) * ((size_t)M * 512) + (size_t)row * 512 + (col & 511); }
; __device__ __forceinline__ size_t a_off(int row, int col, int nks) { return ((size_t)((row >> 8) * nks + (col >> 5)) << 13) + ((row & 255) << 5) + swzc(row, col & 31); }
; template <int EPI>
; __device__ __forceinline__ void gemm_phase(const u16* __restrict__ A0, int nksA, size_t sA, const u16* __restrict__ B0, int nksB, size_t sB,
;                                            int K, int nM, int nN, int nbatch, const EpiArgs ea, char* smem, int bid, int nblk) {
;     ...
;         const int row = brow + wr * 128 + m * 16 + fr, col = bcol + wc * 64 + n * 16 + fq * 4;
;         const f32x4 v = acc[m][n];
;         if (EPI == E_PROJ0) {
;           const uint2 pk = uint2{pk2(v[0], v[1]), pk2(v[2], v[3])};
;           if (bcol < 2048) *(uint2*)(ea.outb + pj_idx(row, col)) = pk;
;           else { const int cc = col - 2048; *(uint2*)(ea.ux + (size_t)(cc >> 4) * S5C * UXW + a_off(row >> 5, (row & 31) * 16 + (cc & 15), 20)) = pk; }
;         }
;         if (EPI == E_BF16) *(uint2*)(ea.outb + (size_t)row * ea.ldc + col) = uint2{pk2(v[0], v[1]), pk2(v[2], v[3])};
;         if (EPI == E_RESID) {
;           const size_t idx = (size_t)row * 1024 + col;
;           const f32x4 r4 = *(const f32x4*)(ea.res + idx), g4 = *(const f32x4*)(ea.gate + (size_t)(row >> 13) * 6144 + col);
;           *(f32x4*)(ea.outf + idx) = f32x4{r4[0] + g4[0] * v[0], r4[1] + g4[1] * v[1], r4[2] + g4[2] * v[2], r4[3] + g4[3] * v[3]};
;         }
;         if (EPI == E_GLU) {
;           const uint2 yy = *(const uint2*)(ea.y5 + a_off(row, col, 16));
;           const f32x4 b4 = *(const f32x4*)(ea.bias + col);
;           const float y0 = __uint_as_float(yy.x << 16), y1 = __uint_as_float(yy.x & 0xffff0000u), y2 = __uint_as_float(yy.y << 16), y3 = __uint_as_float(yy.y & 0xffff0000u);
;           *(uint2*)(ea.outb + a_off(row, 512 + col, 32)) = uint2{pk2(y0 * sigmoid_(v[0] + b4[0]), y1 * sigmoid_(v[1] + b4[1])), pk2(y2 * sigmoid_(v[2] + b4[2]), y3 * sigmoid_(v[3] + b4[3]))};
	v_lshlrev_b32_e32 v208, 16, v204
	v_add_f32_e32 v116, v116, v200
	v_add_f32_e32 v117, v117, v201
	v_add_f32_e32 v118, v118, v202
	v_add_f32_e32 v119, v119, v203
	v_mul_f32_e32 v116, 0xbfb8aa3b, v116
	v_mul_f32_e32 v117, 0xbfb8aa3b, v117
	v_mul_f32_e32 v118, 0xbfb8aa3b, v118
	v_mul_f32_e32 v119, 0xbfb8aa3b, v119
	v_exp_f32_e32 v116, v116
	v_exp_f32_e32 v117, v117
	v_exp_f32_e32 v118, v118
	v_exp_f32_e32 v119, v119
	v_add_f32_e32 v116, 1.0, v116
	v_add_f32_e32 v117, 1.0, v117
	v_add_f32_e32 v118, 1.0, v118
	v_add_f32_e32 v119, 1.0, v119
	v_rcp_f32_e32 v116, v116
	v_rcp_f32_e32 v117, v117
	v_rcp_f32_e32 v118, v118
	v_rcp_f32_e32 v119, v119
	v_and_b32_e32 v209, 0xffff0000, v204
	v_lshlrev_b32_e32 v200, 16, v205
	v_and_b32_e32 v201, 0xffff0000, v205
	v_pk_mul_f32 v[116:117], v[116:117], v[208:209]
	v_pk_mul_f32 v[118:119], v[118:119], v[200:201]
	v_cvt_pk_bf16_f32 v116, v116, v117
	v_cvt_pk_bf16_f32 v117, v118, v119
	v_mov_b32_e32 v250, v174
	v_mov_b32_e32 v251, v175
	v_mov_b32_e32 v252, v116
	v_mov_b32_e32 v253, v117
	global_load_dwordx2 v[204:205], v[176:177], off
	global_load_dwordx4 v[200:203], v[124:125], off offset:192
	global_store_dwordx2 v[250:251], v[252:253], off
	v_add_u32_e32 v116, 0x230, v178
	v_ashrrev_i32_e32 v116, 5, v116
	v_add_u32_e32 v116, v147, v116
	v_ashrrev_i32_e32 v117, 31, v116
	v_lshlrev_b64 v[116:117], 14, v[116:117]
	v_lshl_add_u64 v[116:117], s[62:63], 0, v[116:117]
	v_lshl_add_u64 v[116:117], v[116:117], 0, v[206:207]
	v_lshl_add_u64 v[118:119], v[116:117], 0, v[136:137]
	v_mov_b32_e32 v147, v137
	s_waitcnt vmcnt(1)
	v_lshlrev_b32_e32 v178, 16, v204
	v_add_f32_e32 v112, v112, v200
	v_add_f32_e32 v113, v113, v201
	v_add_f32_e32 v114, v114, v202
	v_add_f32_e32 v115, v115, v203
	v_mul_f32_e32 v112, 0xbfb8aa3b, v112
	v_mul_f32_e32 v113, 0xbfb8aa3b, v113
	v_mul_f32_e32 v114, 0xbfb8aa3b, v114
	v_mul_f32_e32 v115, 0xbfb8aa3b, v115
	v_exp_f32_e32 v112, v112
	v_exp_f32_e32 v113, v113
	v_exp_f32_e32 v114, v114
	v_exp_f32_e32 v115, v115
	v_add_f32_e32 v112, 1.0, v112
	v_add_f32_e32 v113, 1.0, v113
	v_add_f32_e32 v114, 1.0, v114
	v_add_f32_e32 v115, 1.0, v115
	v_rcp_f32_e32 v112, v112
	v_rcp_f32_e32 v113, v113
	v_rcp_f32_e32 v114, v114
	v_rcp_f32_e32 v115, v115
	v_and_b32_e32 v179, 0xffff0000, v204
	v_lshlrev_b32_e32 v200, 16, v205
	v_and_b32_e32 v201, 0xffff0000, v205
	v_pk_mul_f32 v[112:113], v[112:113], v[178:179]
	v_pk_mul_f32 v[114:115], v[114:115], v[200:201]
	v_cvt_pk_bf16_f32 v112, v112, v113
	v_cvt_pk_bf16_f32 v113, v114, v115
	v_mov_b32_e32 v250, v118
	v_mov_b32_e32 v251, v119
	v_mov_b32_e32 v252, v112
	v_mov_b32_e32 v253, v113
	global_load_dwordx2 v[178:179], v[164:165], off offset:1024
	s_nop 0
	global_load_dwordx4 v[112:115], v[154:155], off
	global_store_dwordx2 v[250:251], v[252:253], off
	s_waitcnt vmcnt(1)
	v_lshlrev_b32_e32 v200, 16, v178
	v_add_f32_e32 v108, v108, v112
	v_add_f32_e32 v109, v109, v113
	v_add_f32_e32 v110, v110, v114
	v_add_f32_e32 v111, v111, v115
	v_mul_f32_e32 v108, 0xbfb8aa3b, v108
	v_mul_f32_e32 v109, 0xbfb8aa3b, v109
	v_mul_f32_e32 v110, 0xbfb8aa3b, v110
	v_mul_f32_e32 v111, 0xbfb8aa3b, v111
	v_exp_f32_e32 v108, v108
	v_exp_f32_e32 v109, v109
	v_exp_f32_e32 v110, v110
	v_exp_f32_e32 v111, v111
	v_add_f32_e32 v108, 1.0, v108
	v_add_f32_e32 v109, 1.0, v109
	v_add_f32_e32 v110, 1.0, v110
	v_add_f32_e32 v111, 1.0, v111
	v_rcp_f32_e32 v108, v108
	v_rcp_f32_e32 v109, v109
	v_rcp_f32_e32 v110, v110
	v_rcp_f32_e32 v111, v111
	v_and_b32_e32 v201, 0xffff0000, v178
	v_lshlrev_b32_e32 v112, 16, v179
	v_and_b32_e32 v113, 0xffff0000, v179
	v_pk_mul_f32 v[108:109], v[108:109], v[200:201]
	v_pk_mul_f32 v[110:111], v[110:111], v[112:113]
	v_cvt_pk_bf16_f32 v108, v108, v109
	v_cvt_pk_bf16_f32 v109, v110, v111
	v_mov_b32_e32 v250, v166
	v_mov_b32_e32 v251, v167
	v_mov_b32_e32 v252, v108
	v_mov_b32_e32 v253, v109
	global_load_dwordx2 v[112:113], v[168:169], off offset:1024
	s_nop 0
	global_load_dwordx4 v[108:111], v[124:125], off offset:64
	global_store_dwordx2 v[250:251], v[252:253], off offset:1024
	s_waitcnt vmcnt(1)
	v_lshlrev_b32_e32 v114, 16, v112
	v_add_f32_e32 v104, v104, v108
	v_add_f32_e32 v105, v105, v109
	v_add_f32_e32 v106, v106, v110
	v_add_f32_e32 v107, v107, v111
	v_mul_f32_e32 v104, 0xbfb8aa3b, v104
	v_mul_f32_e32 v105, 0xbfb8aa3b, v105
	v_mul_f32_e32 v106, 0xbfb8aa3b, v106
	v_mul_f32_e32 v107, 0xbfb8aa3b, v107
	v_exp_f32_e32 v104, v104
	v_exp_f32_e32 v105, v105
	v_exp_f32_e32 v106, v106
	v_exp_f32_e32 v107, v107
	v_add_f32_e32 v104, 1.0, v104
	v_add_f32_e32 v105, 1.0, v105
	v_add_f32_e32 v106, 1.0, v106
	v_add_f32_e32 v107, 1.0, v107
	v_rcp_f32_e32 v104, v104
	v_rcp_f32_e32 v105, v105
	v_rcp_f32_e32 v106, v106
	v_rcp_f32_e32 v107, v107
	v_and_b32_e32 v115, 0xffff0000, v112
	v_lshlrev_b32_e32 v108, 16, v113
	v_and_b32_e32 v109, 0xffff0000, v113
	v_pk_mul_f32 v[104:105], v[104:105], v[114:115]
	v_pk_mul_f32 v[106:107], v[106:107], v[108:109]
	v_cvt_pk_bf16_f32 v104, v104, v105
	v_cvt_pk_bf16_f32 v105, v106, v107
	v_mov_b32_e32 v250, v170
	v_mov_b32_e32 v251, v171
	v_mov_b32_e32 v252, v104
	v_mov_b32_e32 v253, v105
	global_load_dwordx2 v[108:109], v[172:173], off offset:1024
	s_nop 0
	global_load_dwordx4 v[104:107], v[124:125], off offset:128
	global_store_dwordx2 v[250:251], v[252:253], off offset:1024
	s_waitcnt vmcnt(1)
; __device__ __forceinline__ unsigned pk2(float a, float b) { f32v2 v = {a, b}; bf16v2 r = __builtin_convertvector(v, bf16v2); return __builtin_bit_cast(unsigned, r); }
; __device__ __forceinline__ float sigmoid_(float x) { return __builtin_amdgcn_rcpf(1.f + __expf(-x)); }
; __device__ __forceinline__ size_t pj_idx(int row, int col) { return (size_t)(col >> 9) * ((size_t)M * 512) + (size_t)row * 512 + (col & 511); }
; __device__ __forceinline__ size_t a_off(int row, int col, int nks) { return ((size_t)((row >> 8) * nks + (col >> 5)) << 13) + ((row & 255) << 5) + swzc(row, col & 31); }
; template <int EPI>
; __device__ __forceinline__ void gemm_phase(const u16* __restrict__ A0, int nksA, size_t sA, const u16* __restrict__ B0, int nksB, size_t sB,
;                                            int K, int nM, int nN, int nbatch, const EpiArgs ea, char* smem, int bid, int nblk) {
;     ...
;         const int row = brow + wr * 128 + m * 16 + fr, col = bcol + wc * 64 + n * 16 + fq * 4;
;         const f32x4 v = acc[m][n];
;         if (EPI == E_PROJ0) {
;           const uint2 pk = uint2{pk2(v[0], v[1]), pk2(v[2], v[3])};
;           if (bcol < 2048) *(uint2*)(ea.outb + pj_idx(row, col)) = pk;
;           else { const int cc = col - 2048; *(uint2*)(ea.ux + (size_t)(cc >> 4) * S5C * UXW + a_off(row >> 5, (row & 31) * 16 + (cc & 15), 20)) = pk; }
;         }
;         if (EPI == E_BF16) *(uint2*)(ea.outb + (size_t)row * ea.ldc + col) = uint2{pk2(v[0], v[1]), pk2(v[2], v[3])};
;         if (EPI == E_RESID) {
;           const size_t idx = (size_t)row * 1024 + col;
;           const f32x4 r4 = *(const f32x4*)(ea.res + idx), g4 = *(const f32x4*)(ea.gate + (size_t)(row >> 13) * 6144 + col);
;           *(f32x4*)(ea.outf + idx) = f32x4{r4[0] + g4[0] * v[0], r4[1] + g4[1] * v[1], r4[2] + g4[2] * v[2], r4[3] + g4[3] * v[3]};
;         }
;         if (EPI == E_GLU) {
;           const uint2 yy = *(const uint2*)(ea.y5 + a_off(row, col, 16));
;           const f32x4 b4 = *(const f32x4*)(ea.bias + col);
;           const float y0 = __uint_as_float(yy.x << 16), y1 = __uint_as_float(yy.x & 0xffff0000u), y2 = __uint_as_float(yy.y << 16), y3 = __uint_as_float(yy.y & 0xffff0000u);
;           *(uint2*)(ea.outb + a_off(row, 512 + col, 32)) = uint2{pk2(y0 * sigmoid_(v[0] + b4[0]), y1 * sigmoid_(v[1] + b4[1])), pk2(y2 * sigmoid_(v[2] + b4[2]), y3 * sigmoid_(v[3] + b4[3]))};
	v_lshlrev_b32_e32 v110, 16, v108
	v_add_f32_e32 v100, v100, v104
	v_add_f32_e32 v101, v101, v105
	v_add_f32_e32 v102, v102, v106
	v_add_f32_e32 v103, v103, v107
	v_mul_f32_e32 v100, 0xbfb8aa3b, v100
	v_mul_f32_e32 v101, 0xbfb8aa3b, v101
	v_mul_f32_e32 v102, 0xbfb8aa3b, v102
	v_mul_f32_e32 v103, 0xbfb8aa3b, v103
	v_exp_f32_e32 v100, v100
	v_exp_f32_e32 v101, v101
	v_exp_f32_e32 v102, v102
	v_exp_f32_e32 v103, v103
	v_add_f32_e32 v100, 1.0, v100
	v_add_f32_e32 v101, 1.0, v101
	v_add_f32_e32 v102, 1.0, v102
	v_add_f32_e32 v103, 1.0, v103
	v_rcp_f32_e32 v100, v100
	v_rcp_f32_e32 v101, v101
	v_rcp_f32_e32 v102, v102
	v_rcp_f32_e32 v103, v103
	v_and_b32_e32 v111, 0xffff0000, v108
	v_lshlrev_b32_e32 v104, 16, v109
	v_and_b32_e32 v105, 0xffff0000, v109
	v_pk_mul_f32 v[100:101], v[100:101], v[110:111]
	v_pk_mul_f32 v[102:103], v[102:103], v[104:105]
	v_cvt_pk_bf16_f32 v100, v100, v101
	v_cvt_pk_bf16_f32 v101, v102, v103
	v_mov_b32_e32 v250, v174
	v_mov_b32_e32 v251, v175
	v_mov_b32_e32 v252, v100
	v_mov_b32_e32 v253, v101
	global_load_dwordx2 v[104:105], v[176:177], off offset:1024
	s_nop 0
	global_load_dwordx4 v[100:103], v[124:125], off offset:192
	global_store_dwordx2 v[250:251], v[252:253], off offset:1024
	s_waitcnt vmcnt(1)
	v_lshlrev_b32_e32 v106, 16, v104
	v_add_f32_e32 v96, v96, v100
	v_add_f32_e32 v97, v97, v101
	v_add_f32_e32 v98, v98, v102
	v_add_f32_e32 v99, v99, v103
	v_mul_f32_e32 v96, 0xbfb8aa3b, v96
	v_mul_f32_e32 v97, 0xbfb8aa3b, v97
	v_mul_f32_e32 v98, 0xbfb8aa3b, v98
	v_mul_f32_e32 v99, 0xbfb8aa3b, v99
	v_exp_f32_e32 v96, v96
	v_exp_f32_e32 v97, v97
	v_exp_f32_e32 v98, v98
	v_exp_f32_e32 v99, v99
	v_add_f32_e32 v96, 1.0, v96
	v_add_f32_e32 v97, 1.0, v97
	v_add_f32_e32 v98, 1.0, v98
	v_add_f32_e32 v99, 1.0, v99
	v_rcp_f32_e32 v96, v96
	v_rcp_f32_e32 v97, v97
	v_rcp_f32_e32 v98, v98
	v_rcp_f32_e32 v99, v99
	v_and_b32_e32 v107, 0xffff0000, v104
	v_lshlrev_b32_e32 v100, 16, v105
	v_and_b32_e32 v101, 0xffff0000, v105
	v_pk_mul_f32 v[96:97], v[96:97], v[106:107]
	v_pk_mul_f32 v[98:99], v[98:99], v[100:101]
	v_cvt_pk_bf16_f32 v96, v96, v97
	v_cvt_pk_bf16_f32 v97, v98, v99
	v_mov_b32_e32 v250, v118
	v_mov_b32_e32 v251, v119
	v_mov_b32_e32 v252, v96
	v_mov_b32_e32 v253, v97
	global_load_dwordx2 v[100:101], v[164:165], off offset:2048
	s_nop 0
	global_load_dwordx4 v[96:99], v[154:155], off
	global_store_dwordx2 v[250:251], v[252:253], off offset:1024
	s_waitcnt vmcnt(1)
	v_lshlrev_b32_e32 v102, 16, v100
	v_add_f32_e32 v92, v92, v96
	v_add_f32_e32 v93, v93, v97
	v_add_f32_e32 v94, v94, v98
	v_add_f32_e32 v95, v95, v99
	v_mul_f32_e32 v92, 0xbfb8aa3b, v92
	v_mul_f32_e32 v93, 0xbfb8aa3b, v93
	v_mul_f32_e32 v94, 0xbfb8aa3b, v94
	v_mul_f32_e32 v95, 0xbfb8aa3b, v95
	v_exp_f32_e32 v92, v92
	v_exp_f32_e32 v93, v93
	v_exp_f32_e32 v94, v94
	v_exp_f32_e32 v95, v95
	v_add_f32_e32 v92, 1.0, v92
	v_add_f32_e32 v93, 1.0, v93
	v_add_f32_e32 v94, 1.0, v94
	v_add_f32_e32 v95, 1.0, v95
	v_rcp_f32_e32 v92, v92
	v_rcp_f32_e32 v93, v93
	v_rcp_f32_e32 v94, v94
	v_rcp_f32_e32 v95, v95
	v_and_b32_e32 v103, 0xffff0000, v100
	v_lshlrev_b32_e32 v96, 16, v101
	v_and_b32_e32 v97, 0xffff0000, v101
	v_pk_mul_f32 v[92:93], v[92:93], v[102:103]
	v_pk_mul_f32 v[94:95], v[94:95], v[96:97]
	v_cvt_pk_bf16_f32 v92, v92, v93
	v_cvt_pk_bf16_f32 v93, v94, v95
	v_mov_b32_e32 v250, v166
	v_mov_b32_e32 v251, v167
	v_mov_b32_e32 v252, v92
	v_mov_b32_e32 v253, v93
	global_load_dwordx2 v[96:97], v[168:169], off offset:2048
	s_nop 0
	global_load_dwordx4 v[92:95], v[124:125], off offset:64
	global_store_dwordx2 v[250:251], v[252:253], off offset:2048
	s_waitcnt vmcnt(1)
	v_lshlrev_b32_e32 v98, 16, v96
	v_add_f32_e32 v88, v88, v92
	v_add_f32_e32 v89, v89, v93
	v_add_f32_e32 v90, v90, v94
	v_add_f32_e32 v91, v91, v95
	v_mul_f32_e32 v88, 0xbfb8aa3b, v88
	v_mul_f32_e32 v89, 0xbfb8aa3b, v89
	v_mul_f32_e32 v90, 0xbfb8aa3b, v90
	v_mul_f32_e32 v91, 0xbfb8aa3b, v91
	v_exp_f32_e32 v88, v88
	v_exp_f32_e32 v89, v89
	v_exp_f32_e32 v90, v90
	v_exp_f32_e32 v91, v91
	v_add_f32_e32 v88, 1.0, v88
	v_add_f32_e32 v89, 1.0, v89
	v_add_f32_e32 v90, 1.0, v90
	v_add_f32_e32 v91, 1.0, v91
	v_rcp_f32_e32 v88, v88
	v_rcp_f32_e32 v89, v89
	v_rcp_f32_e32 v90, v90
	v_rcp_f32_e32 v91, v91
	v_and_b32_e32 v99, 0xffff0000, v96
	v_lshlrev_b32_e32 v92, 16, v97
	v_and_b32_e32 v93, 0xffff0000, v97
	v_pk_mul_f32 v[88:89], v[88:89], v[98:99]
	v_pk_mul_f32 v[90:91], v[90:91], v[92:93]
	v_cvt_pk_bf16_f32 v88, v88, v89
	v_cvt_pk_bf16_f32 v89, v90, v91
	v_mov_b32_e32 v250, v170
	v_mov_b32_e32 v251, v171
	v_mov_b32_e32 v252, v88
	v_mov_b32_e32 v253, v89
	global_load_dwordx2 v[92:93], v[172:173], off offset:2048
	s_nop 0
	global_load_dwordx4 v[88:91], v[124:125], off offset:128
	global_store_dwordx2 v[250:251], v[252:253], off offset:2048
	s_waitcnt vmcnt(1)
	v_lshlrev_b32_e32 v94, 16, v92
	v_add_f32_e32 v84, v84, v88
	v_add_f32_e32 v85, v85, v89
	v_add_f32_e32 v86, v86, v90
	v_add_f32_e32 v87, v87, v91
	v_mul_f32_e32 v84, 0xbfb8aa3b, v84
	v_mul_f32_e32 v85, 0xbfb8aa3b, v85
	v_mul_f32_e32 v86, 0xbfb8aa3b, v86
	v_mul_f32_e32 v87, 0xbfb8aa3b, v87
	v_exp_f32_e32 v84, v84
	v_exp_f32_e32 v85, v85
	v_exp_f32_e32 v86, v86
	v_exp_f32_e32 v87, v87
	v_add_f32_e32 v84, 1.0, v84
	v_add_f32_e32 v85, 1.0, v85
	v_add_f32_e32 v86, 1.0, v86
	v_add_f32_e32 v87, 1.0, v87
	v_rcp_f32_e32 v84, v84
	v_rcp_f32_e32 v85, v85
	v_rcp_f32_e32 v86, v86
	v_rcp_f32_e32 v87, v87
	v_and_b32_e32 v95, 0xffff0000, v92
	v_lshlrev_b32_e32 v88, 16, v93
	v_and_b32_e32 v89, 0xffff0000, v93
	v_pk_mul_f32 v[84:85], v[84:85], v[94:95]
	v_pk_mul_f32 v[86:87], v[86:87], v[88:89]
	v_cvt_pk_bf16_f32 v84, v84, v85
	v_cvt_pk_bf16_f32 v85, v86, v87
	v_mov_b32_e32 v250, v174
	v_mov_b32_e32 v251, v175
	v_mov_b32_e32 v252, v84
	v_mov_b32_e32 v253, v85
	global_load_dwordx2 v[88:89], v[176:177], off offset:2048
	s_nop 0
	global_load_dwordx4 v[84:87], v[124:125], off offset:192
	global_store_dwordx2 v[250:251], v[252:253], off offset:2048
	s_waitcnt vmcnt(1)
; __device__ __forceinline__ unsigned pk2(float a, float b) { f32v2 v = {a, b}; bf16v2 r = __builtin_convertvector(v, bf16v2); return __builtin_bit_cast(unsigned, r); }
; __device__ __forceinline__ float sigmoid_(float x) { return __builtin_amdgcn_rcpf(1.f + __expf(-x)); }
; __device__ __forceinline__ size_t pj_idx(int row, int col) { return (size_t)(col >> 9) * ((size_t)M * 512) + (size_t)row * 512 + (col & 511); }
; __device__ __forceinline__ size_t a_off(int row, int col, int nks) { return ((size_t)((row >> 8) * nks + (col >> 5)) << 13) + ((row & 255) << 5) + swzc(row, col & 31); }
; template <int EPI>
; __device__ __forceinline__ void gemm_phase(const u16* __restrict__ A0, int nksA, size_t sA, const u16* __restrict__ B0, int nksB, size_t sB,
;                                            int K, int nM, int nN, int nbatch, const EpiArgs ea, char* smem, int bid, int nblk) {
;     ...
;         const int row = brow + wr * 128 + m * 16 + fr, col = bcol + wc * 64 + n * 16 + fq * 4;
;         const f32x4 v = acc[m][n];
;         if (EPI == E_PROJ0) {
;           const uint2 pk = uint2{pk2(v[0], v[1]), pk2(v[2], v[3])};
;           if (bcol < 2048) *(uint2*)(ea.outb + pj_idx(row, col)) = pk;
;           else { const int cc = col - 2048; *(uint2*)(ea.ux + (size_t)(cc >> 4) * S5C * UXW + a_off(row >> 5, (row & 31) * 16 + (cc & 15), 20)) = pk; }
;         }
;         if (EPI == E_BF16) *(uint2*)(ea.outb + (size_t)row * ea.ldc + col) = uint2{pk2(v[0], v[1]), pk2(v[2], v[3])};
;         if (EPI == E_RESID) {
;           const size_t idx = (size_t)row * 1024 + col;
;           const f32x4 r4 = *(const f32x4*)(ea.res + idx), g4 = *(const f32x4*)(ea.gate + (size_t)(row >> 13) * 6144 + col);
;           *(f32x4*)(ea.outf + idx) = f32x4{r4[0] + g4[0] * v[0], r4[1] + g4[1] * v[1], r4[2] + g4[2] * v[2], r4[3] + g4[3] * v[3]};
;         }
;         if (EPI == E_GLU) {
;           const uint2 yy = *(const uint2*)(ea.y5 + a_off(row, col, 16));
;           const f32x4 b4 = *(const f32x4*)(ea.bias + col);
;           const float y0 = __uint_as_float(yy.x << 16), y1 = __uint_as_float(yy.x & 0xffff0000u), y2 = __uint_as_float(yy.y << 16), y3 = __uint_as_float(yy.y & 0xffff0000u);
;           *(uint2*)(ea.outb + a_off(row, 512 + col, 32)) = uint2{pk2(y0 * sigmoid_(v[0] + b4[0]), y1 * sigmoid_(v[1] + b4[1])), pk2(y2 * sigmoid_(v[2] + b4[2]), y3 * sigmoid_(v[3] + b4[3]))};
	v_lshlrev_b32_e32 v90, 16, v88
	v_add_f32_e32 v80, v80, v84
	v_add_f32_e32 v81, v81, v85
	v_add_f32_e32 v82, v82, v86
	v_add_f32_e32 v83, v83, v87
	v_mul_f32_e32 v80, 0xbfb8aa3b, v80
	v_mul_f32_e32 v81, 0xbfb8aa3b, v81
	v_mul_f32_e32 v82, 0xbfb8aa3b, v82
	v_mul_f32_e32 v83, 0xbfb8aa3b, v83
	v_exp_f32_e32 v80, v80
	v_exp_f32_e32 v81, v81
	v_exp_f32_e32 v82, v82
	v_exp_f32_e32 v83, v83
	v_add_f32_e32 v80, 1.0, v80
	v_add_f32_e32 v81, 1.0, v81
	v_add_f32_e32 v82, 1.0, v82
	v_add_f32_e32 v83, 1.0, v83
	v_rcp_f32_e32 v80, v80
	v_rcp_f32_e32 v81, v81
	v_rcp_f32_e32 v82, v82
	v_rcp_f32_e32 v83, v83
	v_and_b32_e32 v91, 0xffff0000, v88
	v_lshlrev_b32_e32 v84, 16, v89
	v_and_b32_e32 v85, 0xffff0000, v89
	v_pk_mul_f32 v[80:81], v[80:81], v[90:91]
	v_pk_mul_f32 v[82:83], v[82:83], v[84:85]
	v_cvt_pk_bf16_f32 v80, v80, v81
	v_cvt_pk_bf16_f32 v81, v82, v83
	v_mov_b32_e32 v250, v118
	v_mov_b32_e32 v251, v119
	v_mov_b32_e32 v252, v80
	v_mov_b32_e32 v253, v81
	global_load_dwordx2 v[84:85], v[164:165], off offset:3072
	s_nop 0
	global_load_dwordx4 v[80:83], v[154:155], off
	global_store_dwordx2 v[250:251], v[252:253], off offset:2048
	s_waitcnt vmcnt(1)
	v_lshlrev_b32_e32 v86, 16, v84
	v_add_f32_e32 v76, v76, v80
	v_add_f32_e32 v77, v77, v81
	v_add_f32_e32 v78, v78, v82
	v_add_f32_e32 v79, v79, v83
	v_mul_f32_e32 v76, 0xbfb8aa3b, v76
	v_mul_f32_e32 v77, 0xbfb8aa3b, v77
	v_mul_f32_e32 v78, 0xbfb8aa3b, v78
	v_mul_f32_e32 v79, 0xbfb8aa3b, v79
	v_exp_f32_e32 v76, v76
	v_exp_f32_e32 v77, v77
	v_exp_f32_e32 v78, v78
	v_exp_f32_e32 v79, v79
	v_add_f32_e32 v76, 1.0, v76
	v_add_f32_e32 v77, 1.0, v77
	v_add_f32_e32 v78, 1.0, v78
	v_add_f32_e32 v79, 1.0, v79
	v_rcp_f32_e32 v76, v76
	v_rcp_f32_e32 v77, v77
	v_rcp_f32_e32 v78, v78
	v_rcp_f32_e32 v79, v79
	v_and_b32_e32 v87, 0xffff0000, v84
	v_lshlrev_b32_e32 v80, 16, v85
	v_and_b32_e32 v81, 0xffff0000, v85
	v_pk_mul_f32 v[76:77], v[76:77], v[86:87]
	v_pk_mul_f32 v[78:79], v[78:79], v[80:81]
	v_cvt_pk_bf16_f32 v76, v76, v77
	v_cvt_pk_bf16_f32 v77, v78, v79
	v_mov_b32_e32 v250, v166
	v_mov_b32_e32 v251, v167
	v_mov_b32_e32 v252, v76
	v_mov_b32_e32 v253, v77
	global_load_dwordx2 v[80:81], v[168:169], off offset:3072
	s_nop 0
	global_load_dwordx4 v[76:79], v[124:125], off offset:64
	global_store_dwordx2 v[250:251], v[252:253], off offset:3072
	s_waitcnt vmcnt(1)
	v_lshlrev_b32_e32 v82, 16, v80
	v_add_f32_e32 v72, v72, v76
	v_add_f32_e32 v73, v73, v77
	v_add_f32_e32 v74, v74, v78
	v_add_f32_e32 v75, v75, v79
	v_mul_f32_e32 v72, 0xbfb8aa3b, v72
	v_mul_f32_e32 v73, 0xbfb8aa3b, v73
	v_mul_f32_e32 v74, 0xbfb8aa3b, v74
	v_mul_f32_e32 v75, 0xbfb8aa3b, v75
	v_exp_f32_e32 v72, v72
	v_exp_f32_e32 v73, v73
	v_exp_f32_e32 v74, v74
	v_exp_f32_e32 v75, v75
	v_add_f32_e32 v72, 1.0, v72
	v_add_f32_e32 v73, 1.0, v73
	v_add_f32_e32 v74, 1.0, v74
	v_add_f32_e32 v75, 1.0, v75
	v_rcp_f32_e32 v72, v72
	v_rcp_f32_e32 v73, v73
	v_rcp_f32_e32 v74, v74
	v_rcp_f32_e32 v75, v75
	v_and_b32_e32 v83, 0xffff0000, v80
	v_lshlrev_b32_e32 v76, 16, v81
	v_and_b32_e32 v77, 0xffff0000, v81
	v_pk_mul_f32 v[72:73], v[72:73], v[82:83]
	v_pk_mul_f32 v[74:75], v[74:75], v[76:77]
	v_cvt_pk_bf16_f32 v72, v72, v73
	v_cvt_pk_bf16_f32 v73, v74, v75
	v_mov_b32_e32 v250, v170
	v_mov_b32_e32 v251, v171
	v_mov_b32_e32 v252, v72
	v_mov_b32_e32 v253, v73
	global_load_dwordx2 v[76:77], v[172:173], off offset:3072
	s_nop 0
	global_load_dwordx4 v[72:75], v[124:125], off offset:128
	global_store_dwordx2 v[250:251], v[252:253], off offset:3072
	s_waitcnt vmcnt(1)
	v_lshlrev_b32_e32 v78, 16, v76
	v_add_f32_e32 v68, v68, v72
	v_add_f32_e32 v69, v69, v73
	v_add_f32_e32 v70, v70, v74
	v_add_f32_e32 v71, v71, v75
	v_mul_f32_e32 v68, 0xbfb8aa3b, v68
	v_mul_f32_e32 v69, 0xbfb8aa3b, v69
	v_mul_f32_e32 v70, 0xbfb8aa3b, v70
	v_mul_f32_e32 v71, 0xbfb8aa3b, v71
	v_exp_f32_e32 v68, v68
	v_exp_f32_e32 v69, v69
	v_exp_f32_e32 v70, v70
	v_exp_f32_e32 v71, v71
	v_add_f32_e32 v68, 1.0, v68
	v_add_f32_e32 v69, 1.0, v69
	v_add_f32_e32 v70, 1.0, v70
	v_add_f32_e32 v71, 1.0, v71
	v_rcp_f32_e32 v68, v68
	v_rcp_f32_e32 v69, v69
	v_rcp_f32_e32 v70, v70
	v_rcp_f32_e32 v71, v71
	v_and_b32_e32 v79, 0xffff0000, v76
	v_lshlrev_b32_e32 v72, 16, v77
	v_and_b32_e32 v73, 0xffff0000, v77
	v_pk_mul_f32 v[68:69], v[68:69], v[78:79]
	v_pk_mul_f32 v[70:71], v[70:71], v[72:73]
	v_cvt_pk_bf16_f32 v68, v68, v69
	v_cvt_pk_bf16_f32 v69, v70, v71
	v_mov_b32_e32 v250, v174
	v_mov_b32_e32 v251, v175
	v_mov_b32_e32 v252, v68
	v_mov_b32_e32 v253, v69
	global_load_dwordx2 v[72:73], v[176:177], off offset:3072
	s_nop 0
	global_load_dwordx4 v[68:71], v[124:125], off offset:192
	global_store_dwordx2 v[250:251], v[252:253], off offset:3072
	v_lshl_add_u64 v[74:75], v[160:161], 0, v[146:147]
	s_waitcnt vmcnt(1)
	v_lshlrev_b32_e32 v76, 16, v72
	v_add_f32_e32 v64, v64, v68
	v_add_f32_e32 v65, v65, v69
	v_add_f32_e32 v66, v66, v70
	v_add_f32_e32 v67, v67, v71
	v_mul_f32_e32 v64, 0xbfb8aa3b, v64
	v_mul_f32_e32 v65, 0xbfb8aa3b, v65
	v_mul_f32_e32 v66, 0xbfb8aa3b, v66
	v_mul_f32_e32 v67, 0xbfb8aa3b, v67
	v_exp_f32_e32 v64, v64
	v_exp_f32_e32 v65, v65
	v_exp_f32_e32 v66, v66
	v_exp_f32_e32 v67, v67
	v_add_f32_e32 v64, 1.0, v64
	v_add_f32_e32 v65, 1.0, v65
	v_add_f32_e32 v66, 1.0, v66
	v_add_f32_e32 v67, 1.0, v67
	v_rcp_f32_e32 v64, v64
	v_rcp_f32_e32 v65, v65
	v_rcp_f32_e32 v66, v66
	v_rcp_f32_e32 v67, v67
	v_and_b32_e32 v77, 0xffff0000, v72
	v_lshlrev_b32_e32 v68, 16, v73
	v_and_b32_e32 v69, 0xffff0000, v73
	v_pk_mul_f32 v[64:65], v[64:65], v[76:77]
	v_pk_mul_f32 v[66:67], v[66:67], v[68:69]
	v_cvt_pk_bf16_f32 v64, v64, v65
	v_cvt_pk_bf16_f32 v65, v66, v67
	v_mov_b32_e32 v250, v118
	v_mov_b32_e32 v251, v119
	v_mov_b32_e32 v252, v64
	v_mov_b32_e32 v253, v65
	global_load_dwordx2 v[68:69], v[74:75], off
	s_nop 0
	global_load_dwordx4 v[64:67], v[154:155], off
	global_store_dwordx2 v[250:251], v[252:253], off offset:3072
	v_lshl_add_u64 v[70:71], v[158:159], 0, v[146:147]
	v_lshl_add_u64 v[72:73], v[156:157], 0, v[146:147]
	s_waitcnt vmcnt(1)
; __device__ __forceinline__ unsigned pk2(float a, float b) { f32v2 v = {a, b}; bf16v2 r = __builtin_convertvector(v, bf16v2); return __builtin_bit_cast(unsigned, r); }
; __device__ __forceinline__ float sigmoid_(float x) { return __builtin_amdgcn_rcpf(1.f + __expf(-x)); }
; __device__ __forceinline__ size_t a_off(int row, int col, int nks) { return ((size_t)((row >> 8) * nks + (col >> 5)) << 13) + ((row & 255) << 5) + swzc(row, col & 31); }
; template <int EPI>
; __device__ __forceinline__ void gemm_phase(const u16* __restrict__ A0, int nksA, size_t sA, const u16* __restrict__ B0, int nksB, size_t sB,
;                                            int K, int nM, int nN, int nbatch, const EpiArgs ea, char* smem, int bid, int nblk) {
;     ...
;         if (EPI == E_GLU) {
;           const uint2 yy = *(const uint2*)(ea.y5 + a_off(row, col, 16));
;           const f32x4 b4 = *(const f32x4*)(ea.bias + col);
;           const float y0 = __uint_as_float(yy.x << 16), y1 = __uint_as_float(yy.x & 0xffff0000u), y2 = __uint_as_float(yy.y << 16), y3 = __uint_as_float(yy.y & 0xffff0000u);
;           *(uint2*)(ea.outb + a_off(row, 512 + col, 32)) = uint2{pk2(y0 * sigmoid_(v[0] + b4[0]), y1 * sigmoid_(v[1] + b4[1])), pk2(y2 * sigmoid_(v[2] + b4[2]), y3 * sigmoid_(v[3] + b4[3]))};
	v_lshlrev_b32_e32 v74, 16, v68
	v_add_f32_e32 v60, v60, v64
	v_add_f32_e32 v61, v61, v65
	v_add_f32_e32 v62, v62, v66
	v_add_f32_e32 v63, v63, v67
	v_mul_f32_e32 v60, 0xbfb8aa3b, v60
	v_mul_f32_e32 v61, 0xbfb8aa3b, v61
	v_mul_f32_e32 v62, 0xbfb8aa3b, v62
	v_mul_f32_e32 v63, 0xbfb8aa3b, v63
	v_exp_f32_e32 v60, v60
	v_exp_f32_e32 v61, v61
	v_exp_f32_e32 v62, v62
	v_exp_f32_e32 v63, v63
	v_add_f32_e32 v60, 1.0, v60
	v_add_f32_e32 v61, 1.0, v61
	v_add_f32_e32 v62, 1.0, v62
	v_add_f32_e32 v63, 1.0, v63
	v_rcp_f32_e32 v60, v60
	v_rcp_f32_e32 v61, v61
	v_rcp_f32_e32 v62, v62
	v_rcp_f32_e32 v63, v63
	v_and_b32_e32 v75, 0xffff0000, v68
	v_lshlrev_b32_e32 v64, 16, v69
	v_and_b32_e32 v65, 0xffff0000, v69
	v_pk_mul_f32 v[60:61], v[60:61], v[74:75]
	v_pk_mul_f32 v[62:63], v[62:63], v[64:65]
	v_cvt_pk_bf16_f32 v60, v60, v61
	v_cvt_pk_bf16_f32 v61, v62, v63
	v_mov_b32_e32 v250, v70
	v_mov_b32_e32 v251, v71
	v_mov_b32_e32 v252, v60
	v_mov_b32_e32 v253, v61
	global_load_dwordx2 v[64:65], v[72:73], off
	s_nop 0
	global_load_dwordx4 v[60:63], v[124:125], off offset:64
	global_store_dwordx2 v[250:251], v[252:253], off
	v_lshl_add_u64 v[66:67], v[162:163], 0, v[146:147]
	v_lshl_add_u64 v[68:69], v[126:127], 0, v[146:147]
	s_waitcnt vmcnt(1)
	v_lshlrev_b32_e32 v70, 16, v64
	v_add_f32_e32 v56, v56, v60
	v_add_f32_e32 v57, v57, v61
	v_add_f32_e32 v58, v58, v62
	v_add_f32_e32 v59, v59, v63
	v_mul_f32_e32 v56, 0xbfb8aa3b, v56
	v_mul_f32_e32 v57, 0xbfb8aa3b, v57
	v_mul_f32_e32 v58, 0xbfb8aa3b, v58
	v_mul_f32_e32 v59, 0xbfb8aa3b, v59
	v_exp_f32_e32 v56, v56
	v_exp_f32_e32 v57, v57
	v_exp_f32_e32 v58, v58
	v_exp_f32_e32 v59, v59
	v_add_f32_e32 v56, 1.0, v56
	v_add_f32_e32 v57, 1.0, v57
	v_add_f32_e32 v58, 1.0, v58
	v_add_f32_e32 v59, 1.0, v59
	v_rcp_f32_e32 v56, v56
	v_rcp_f32_e32 v57, v57
	v_rcp_f32_e32 v58, v58
	v_rcp_f32_e32 v59, v59
	v_and_b32_e32 v71, 0xffff0000, v64
	v_lshlrev_b32_e32 v60, 16, v65
	v_and_b32_e32 v61, 0xffff0000, v65
	v_pk_mul_f32 v[56:57], v[56:57], v[70:71]
	v_pk_mul_f32 v[58:59], v[58:59], v[60:61]
	v_cvt_pk_bf16_f32 v56, v56, v57
	v_cvt_pk_bf16_f32 v57, v58, v59
	v_mov_b32_e32 v250, v66
	v_mov_b32_e32 v251, v67
	v_mov_b32_e32 v252, v56
	v_mov_b32_e32 v253, v57
	global_load_dwordx2 v[60:61], v[68:69], off
	s_nop 0
	global_load_dwordx4 v[56:59], v[124:125], off offset:128
	global_store_dwordx2 v[250:251], v[252:253], off
	v_lshl_add_u64 v[62:63], v[122:123], 0, v[146:147]
	v_lshl_add_u64 v[64:65], v[120:121], 0, v[146:147]
	s_waitcnt vmcnt(1)
	v_lshlrev_b32_e32 v66, 16, v60
	v_add_f32_e32 v52, v52, v56
	v_add_f32_e32 v53, v53, v57
	v_add_f32_e32 v54, v54, v58
	v_add_f32_e32 v55, v55, v59
	v_mul_f32_e32 v52, 0xbfb8aa3b, v52
	v_mul_f32_e32 v53, 0xbfb8aa3b, v53
	v_mul_f32_e32 v54, 0xbfb8aa3b, v54
	v_mul_f32_e32 v55, 0xbfb8aa3b, v55
	v_exp_f32_e32 v52, v52
	v_exp_f32_e32 v53, v53
	v_exp_f32_e32 v54, v54
	v_exp_f32_e32 v55, v55
	v_add_f32_e32 v52, 1.0, v52
	v_add_f32_e32 v53, 1.0, v53
	v_add_f32_e32 v54, 1.0, v54
	v_add_f32_e32 v55, 1.0, v55
	v_rcp_f32_e32 v52, v52
	v_rcp_f32_e32 v53, v53
	v_rcp_f32_e32 v54, v54
	v_rcp_f32_e32 v55, v55
	v_and_b32_e32 v67, 0xffff0000, v60
	v_lshlrev_b32_e32 v56, 16, v61
	v_and_b32_e32 v57, 0xffff0000, v61
	v_pk_mul_f32 v[52:53], v[52:53], v[66:67]
	v_pk_mul_f32 v[54:55], v[54:55], v[56:57]
	v_cvt_pk_bf16_f32 v52, v52, v53
	v_cvt_pk_bf16_f32 v53, v54, v55
	v_mov_b32_e32 v250, v62
	v_mov_b32_e32 v251, v63
	v_mov_b32_e32 v252, v52
	v_mov_b32_e32 v253, v53
	global_load_dwordx2 v[56:57], v[64:65], off
	s_nop 0
	global_load_dwordx4 v[52:55], v[124:125], off offset:192
	global_store_dwordx2 v[250:251], v[252:253], off
	v_lshl_add_u64 v[60:61], v[116:117], 0, v[146:147]
	v_lshl_add_u64 v[58:59], v[160:161], 0, v[148:149]
	s_waitcnt vmcnt(1)
	v_lshlrev_b32_e32 v62, 16, v56
	v_add_f32_e32 v48, v48, v52
	v_add_f32_e32 v49, v49, v53
	v_add_f32_e32 v50, v50, v54
	v_add_f32_e32 v51, v51, v55
	v_mul_f32_e32 v48, 0xbfb8aa3b, v48
	v_mul_f32_e32 v49, 0xbfb8aa3b, v49
	v_mul_f32_e32 v50, 0xbfb8aa3b, v50
	v_mul_f32_e32 v51, 0xbfb8aa3b, v51
	v_exp_f32_e32 v48, v48
	v_exp_f32_e32 v49, v49
	v_exp_f32_e32 v50, v50
	v_exp_f32_e32 v51, v51
	v_add_f32_e32 v48, 1.0, v48
	v_add_f32_e32 v49, 1.0, v49
	v_add_f32_e32 v50, 1.0, v50
	v_add_f32_e32 v51, 1.0, v51
	v_rcp_f32_e32 v48, v48
	v_rcp_f32_e32 v49, v49
	v_rcp_f32_e32 v50, v50
	v_rcp_f32_e32 v51, v51
	v_and_b32_e32 v63, 0xffff0000, v56
	v_lshlrev_b32_e32 v52, 16, v57
	v_and_b32_e32 v53, 0xffff0000, v57
	v_pk_mul_f32 v[48:49], v[48:49], v[62:63]
	v_pk_mul_f32 v[50:51], v[50:51], v[52:53]
	v_cvt_pk_bf16_f32 v48, v48, v49
	v_cvt_pk_bf16_f32 v49, v50, v51
	v_mov_b32_e32 v250, v60
	v_mov_b32_e32 v251, v61
	v_mov_b32_e32 v252, v48
	v_mov_b32_e32 v253, v49
	global_load_dwordx2 v[52:53], v[58:59], off
	s_nop 0
	global_load_dwordx4 v[48:51], v[154:155], off
	global_store_dwordx2 v[250:251], v[252:253], off
	v_lshl_add_u64 v[54:55], v[158:159], 0, v[148:149]
	v_lshl_add_u64 v[56:57], v[156:157], 0, v[148:149]
	s_waitcnt vmcnt(1)
	v_lshlrev_b32_e32 v58, 16, v52
	v_add_f32_e32 v44, v44, v48
	v_add_f32_e32 v45, v45, v49
	v_add_f32_e32 v46, v46, v50
	v_add_f32_e32 v47, v47, v51
	v_mul_f32_e32 v44, 0xbfb8aa3b, v44
	v_mul_f32_e32 v45, 0xbfb8aa3b, v45
	v_mul_f32_e32 v46, 0xbfb8aa3b, v46
	v_mul_f32_e32 v47, 0xbfb8aa3b, v47
	v_exp_f32_e32 v44, v44
	v_exp_f32_e32 v45, v45
	v_exp_f32_e32 v46, v46
	v_exp_f32_e32 v47, v47
	v_add_f32_e32 v44, 1.0, v44
	v_add_f32_e32 v45, 1.0, v45
	v_add_f32_e32 v46, 1.0, v46
	v_add_f32_e32 v47, 1.0, v47
	v_rcp_f32_e32 v44, v44
	v_rcp_f32_e32 v45, v45
	v_rcp_f32_e32 v46, v46
	v_rcp_f32_e32 v47, v47
	v_and_b32_e32 v59, 0xffff0000, v52
	v_lshlrev_b32_e32 v48, 16, v53
	v_and_b32_e32 v49, 0xffff0000, v53
	v_pk_mul_f32 v[44:45], v[44:45], v[58:59]
	v_pk_mul_f32 v[46:47], v[46:47], v[48:49]
	v_cvt_pk_bf16_f32 v44, v44, v45
	v_cvt_pk_bf16_f32 v45, v46, v47
	v_mov_b32_e32 v250, v54
	v_mov_b32_e32 v251, v55
	v_mov_b32_e32 v252, v44
	v_mov_b32_e32 v253, v45
	global_load_dwordx2 v[48:49], v[56:57], off
	s_nop 0
	global_load_dwordx4 v[44:47], v[124:125], off offset:64
	global_store_dwordx2 v[250:251], v[252:253], off
	v_lshl_add_u64 v[50:51], v[162:163], 0, v[148:149]
	v_lshl_add_u64 v[52:53], v[126:127], 0, v[148:149]
	s_waitcnt vmcnt(1)
; __device__ __forceinline__ unsigned pk2(float a, float b) { f32v2 v = {a, b}; bf16v2 r = __builtin_convertvector(v, bf16v2); return __builtin_bit_cast(unsigned, r); }
; __device__ __forceinline__ float sigmoid_(float x) { return __builtin_amdgcn_rcpf(1.f + __expf(-x)); }
; __device__ __forceinline__ size_t a_off(int row, int col, int nks) { return ((size_t)((row >> 8) * nks + (col >> 5)) << 13) + ((row & 255) << 5) + swzc(row, col & 31); }
; template <int EPI>
; __device__ __forceinline__ void gemm_phase(const u16* __restrict__ A0, int nksA, size_t sA, const u16* __restrict__ B0, int nksB, size_t sB,
;                                            int K, int nM, int nN, int nbatch, const EpiArgs ea, char* smem, int bid, int nblk) {
;     ...
;         if (EPI == E_GLU) {
;           const uint2 yy = *(const uint2*)(ea.y5 + a_off(row, col, 16));
;           const f32x4 b4 = *(const f32x4*)(ea.bias + col);
;           const float y0 = __uint_as_float(yy.x << 16), y1 = __uint_as_float(yy.x & 0xffff0000u), y2 = __uint_as_float(yy.y << 16), y3 = __uint_as_float(yy.y & 0xffff0000u);
;           *(uint2*)(ea.outb + a_off(row, 512 + col, 32)) = uint2{pk2(y0 * sigmoid_(v[0] + b4[0]), y1 * sigmoid_(v[1] + b4[1])), pk2(y2 * sigmoid_(v[2] + b4[2]), y3 * sigmoid_(v[3] + b4[3]))};
	v_lshlrev_b32_e32 v54, 16, v48
	v_add_f32_e32 v40, v40, v44
	v_add_f32_e32 v41, v41, v45
	v_add_f32_e32 v42, v42, v46
	v_add_f32_e32 v43, v43, v47
	v_mul_f32_e32 v40, 0xbfb8aa3b, v40
	v_mul_f32_e32 v41, 0xbfb8aa3b, v41
	v_mul_f32_e32 v42, 0xbfb8aa3b, v42
	v_mul_f32_e32 v43, 0xbfb8aa3b, v43
	v_exp_f32_e32 v40, v40
	v_exp_f32_e32 v41, v41
	v_exp_f32_e32 v42, v42
	v_exp_f32_e32 v43, v43
	v_add_f32_e32 v40, 1.0, v40
	v_add_f32_e32 v41, 1.0, v41
	v_add_f32_e32 v42, 1.0, v42
	v_add_f32_e32 v43, 1.0, v43
	v_rcp_f32_e32 v40, v40
	v_rcp_f32_e32 v41, v41
	v_rcp_f32_e32 v42, v42
	v_rcp_f32_e32 v43, v43
	v_and_b32_e32 v55, 0xffff0000, v48
	v_lshlrev_b32_e32 v44, 16, v49
	v_and_b32_e32 v45, 0xffff0000, v49
	v_pk_mul_f32 v[40:41], v[40:41], v[54:55]
	v_pk_mul_f32 v[42:43], v[42:43], v[44:45]
	v_cvt_pk_bf16_f32 v40, v40, v41
	v_cvt_pk_bf16_f32 v41, v42, v43
	v_mov_b32_e32 v250, v50
	v_mov_b32_e32 v251, v51
	v_mov_b32_e32 v252, v40
	v_mov_b32_e32 v253, v41
	global_load_dwordx2 v[44:45], v[52:53], off
	s_nop 0
	global_load_dwordx4 v[40:43], v[124:125], off offset:128
	global_store_dwordx2 v[250:251], v[252:253], off
	v_lshl_add_u64 v[46:47], v[122:123], 0, v[148:149]
	v_lshl_add_u64 v[48:49], v[120:121], 0, v[148:149]
	s_waitcnt vmcnt(1)
	v_lshlrev_b32_e32 v50, 16, v44
	v_add_f32_e32 v36, v36, v40
	v_add_f32_e32 v37, v37, v41
	v_add_f32_e32 v38, v38, v42
	v_add_f32_e32 v39, v39, v43
	v_mul_f32_e32 v36, 0xbfb8aa3b, v36
	v_mul_f32_e32 v37, 0xbfb8aa3b, v37
	v_mul_f32_e32 v38, 0xbfb8aa3b, v38
	v_mul_f32_e32 v39, 0xbfb8aa3b, v39
	v_exp_f32_e32 v36, v36
	v_exp_f32_e32 v37, v37
	v_exp_f32_e32 v38, v38
	v_exp_f32_e32 v39, v39
	v_add_f32_e32 v36, 1.0, v36
	v_add_f32_e32 v37, 1.0, v37
	v_add_f32_e32 v38, 1.0, v38
	v_add_f32_e32 v39, 1.0, v39
	v_rcp_f32_e32 v36, v36
	v_rcp_f32_e32 v37, v37
	v_rcp_f32_e32 v38, v38
	v_rcp_f32_e32 v39, v39
	v_and_b32_e32 v51, 0xffff0000, v44
	v_lshlrev_b32_e32 v40, 16, v45
	v_and_b32_e32 v41, 0xffff0000, v45
	v_pk_mul_f32 v[36:37], v[36:37], v[50:51]
	v_pk_mul_f32 v[38:39], v[38:39], v[40:41]
	v_cvt_pk_bf16_f32 v36, v36, v37
	v_cvt_pk_bf16_f32 v37, v38, v39
	v_mov_b32_e32 v250, v46
	v_mov_b32_e32 v251, v47
	v_mov_b32_e32 v252, v36
	v_mov_b32_e32 v253, v37
	global_load_dwordx2 v[40:41], v[48:49], off
	s_nop 0
	global_load_dwordx4 v[36:39], v[124:125], off offset:192
	global_store_dwordx2 v[250:251], v[252:253], off
	v_lshl_add_u64 v[44:45], v[116:117], 0, v[148:149]
	v_lshl_add_u64 v[42:43], v[160:161], 0, v[150:151]
	s_waitcnt vmcnt(1)
	v_lshlrev_b32_e32 v46, 16, v40
	v_add_f32_e32 v32, v32, v36
	v_add_f32_e32 v33, v33, v37
	v_add_f32_e32 v34, v34, v38
	v_add_f32_e32 v35, v35, v39
	v_mul_f32_e32 v32, 0xbfb8aa3b, v32
	v_mul_f32_e32 v33, 0xbfb8aa3b, v33
	v_mul_f32_e32 v34, 0xbfb8aa3b, v34
	v_mul_f32_e32 v35, 0xbfb8aa3b, v35
	v_exp_f32_e32 v32, v32
	v_exp_f32_e32 v33, v33
	v_exp_f32_e32 v34, v34
	v_exp_f32_e32 v35, v35
	v_add_f32_e32 v32, 1.0, v32
	v_add_f32_e32 v33, 1.0, v33
	v_add_f32_e32 v34, 1.0, v34
	v_add_f32_e32 v35, 1.0, v35
	v_rcp_f32_e32 v32, v32
	v_rcp_f32_e32 v33, v33
	v_rcp_f32_e32 v34, v34
	v_rcp_f32_e32 v35, v35
	v_and_b32_e32 v47, 0xffff0000, v40
	v_lshlrev_b32_e32 v36, 16, v41
	v_and_b32_e32 v37, 0xffff0000, v41
	v_pk_mul_f32 v[32:33], v[32:33], v[46:47]
	v_pk_mul_f32 v[34:35], v[34:35], v[36:37]
	v_cvt_pk_bf16_f32 v32, v32, v33
	v_cvt_pk_bf16_f32 v33, v34, v35
	v_mov_b32_e32 v250, v44
	v_mov_b32_e32 v251, v45
	v_mov_b32_e32 v252, v32
	v_mov_b32_e32 v253, v33
	global_load_dwordx2 v[36:37], v[42:43], off
	s_nop 0
	global_load_dwordx4 v[32:35], v[154:155], off
	global_store_dwordx2 v[250:251], v[252:253], off
	v_lshl_add_u64 v[38:39], v[158:159], 0, v[150:151]
	v_lshl_add_u64 v[40:41], v[156:157], 0, v[150:151]
	s_waitcnt vmcnt(1)
	v_lshlrev_b32_e32 v42, 16, v36
	v_add_f32_e32 v28, v28, v32
	v_add_f32_e32 v29, v29, v33
	v_add_f32_e32 v30, v30, v34
	v_add_f32_e32 v31, v31, v35
	v_mul_f32_e32 v28, 0xbfb8aa3b, v28
	v_mul_f32_e32 v29, 0xbfb8aa3b, v29
	v_mul_f32_e32 v30, 0xbfb8aa3b, v30
	v_mul_f32_e32 v31, 0xbfb8aa3b, v31
	v_exp_f32_e32 v28, v28
	v_exp_f32_e32 v29, v29
	v_exp_f32_e32 v30, v30
	v_exp_f32_e32 v31, v31
	v_add_f32_e32 v28, 1.0, v28
	v_add_f32_e32 v29, 1.0, v29
	v_add_f32_e32 v30, 1.0, v30
	v_add_f32_e32 v31, 1.0, v31
	v_rcp_f32_e32 v28, v28
	v_rcp_f32_e32 v29, v29
	v_rcp_f32_e32 v30, v30
	v_rcp_f32_e32 v31, v31
	v_and_b32_e32 v43, 0xffff0000, v36
	v_lshlrev_b32_e32 v32, 16, v37
	v_and_b32_e32 v33, 0xffff0000, v37
	v_pk_mul_f32 v[28:29], v[28:29], v[42:43]
	v_pk_mul_f32 v[30:31], v[30:31], v[32:33]
	v_cvt_pk_bf16_f32 v28, v28, v29
	v_cvt_pk_bf16_f32 v29, v30, v31
	v_mov_b32_e32 v250, v38
	v_mov_b32_e32 v251, v39
	v_mov_b32_e32 v252, v28
	v_mov_b32_e32 v253, v29
	global_load_dwordx2 v[32:33], v[40:41], off
	s_nop 0
	global_load_dwordx4 v[28:31], v[124:125], off offset:64
	global_store_dwordx2 v[250:251], v[252:253], off
	v_lshl_add_u64 v[34:35], v[162:163], 0, v[150:151]
	v_lshl_add_u64 v[36:37], v[126:127], 0, v[150:151]
	s_waitcnt vmcnt(1)
	v_lshlrev_b32_e32 v38, 16, v32
	v_add_f32_e32 v24, v24, v28
	v_add_f32_e32 v25, v25, v29
	v_add_f32_e32 v26, v26, v30
	v_add_f32_e32 v27, v27, v31
	v_mul_f32_e32 v24, 0xbfb8aa3b, v24
	v_mul_f32_e32 v25, 0xbfb8aa3b, v25
	v_mul_f32_e32 v26, 0xbfb8aa3b, v26
	v_mul_f32_e32 v27, 0xbfb8aa3b, v27
	v_exp_f32_e32 v24, v24
	v_exp_f32_e32 v25, v25
	v_exp_f32_e32 v26, v26
	v_exp_f32_e32 v27, v27
	v_add_f32_e32 v24, 1.0, v24
	v_add_f32_e32 v25, 1.0, v25
	v_add_f32_e32 v26, 1.0, v26
	v_add_f32_e32 v27, 1.0, v27
	v_rcp_f32_e32 v24, v24
	v_rcp_f32_e32 v25, v25
	v_rcp_f32_e32 v26, v26
	v_rcp_f32_e32 v27, v27
	v_and_b32_e32 v39, 0xffff0000, v32
	v_lshlrev_b32_e32 v28, 16, v33
	v_and_b32_e32 v29, 0xffff0000, v33
	v_pk_mul_f32 v[24:25], v[24:25], v[38:39]
	v_pk_mul_f32 v[26:27], v[26:27], v[28:29]
	v_cvt_pk_bf16_f32 v24, v24, v25
	v_cvt_pk_bf16_f32 v25, v26, v27
	v_mov_b32_e32 v250, v34
	v_mov_b32_e32 v251, v35
	v_mov_b32_e32 v252, v24
	v_mov_b32_e32 v253, v25
	global_load_dwordx2 v[28:29], v[36:37], off
	s_nop 0
	global_load_dwordx4 v[24:27], v[124:125], off offset:128
	global_store_dwordx2 v[250:251], v[252:253], off
	v_lshl_add_u64 v[30:31], v[122:123], 0, v[150:151]
	v_lshl_add_u64 v[32:33], v[120:121], 0, v[150:151]
	s_waitcnt vmcnt(1)
; __device__ __forceinline__ unsigned pk2(float a, float b) { f32v2 v = {a, b}; bf16v2 r = __builtin_convertvector(v, bf16v2); return __builtin_bit_cast(unsigned, r); }
; __device__ __forceinline__ float sigmoid_(float x) { return __builtin_amdgcn_rcpf(1.f + __expf(-x)); }
; __device__ __forceinline__ size_t a_off(int row, int col, int nks) { return ((size_t)((row >> 8) * nks + (col >> 5)) << 13) + ((row & 255) << 5) + swzc(row, col & 31); }
; template <int EPI>
; __device__ __forceinline__ void gemm_phase(const u16* __restrict__ A0, int nksA, size_t sA, const u16* __restrict__ B0, int nksB, size_t sB,
;                                            int K, int nM, int nN, int nbatch, const EpiArgs ea, char* smem, int bid, int nblk) {
;     ...
;         if (EPI == E_GLU) {
;           const uint2 yy = *(const uint2*)(ea.y5 + a_off(row, col, 16));
;           const f32x4 b4 = *(const f32x4*)(ea.bias + col);
;           const float y0 = __uint_as_float(yy.x << 16), y1 = __uint_as_float(yy.x & 0xffff0000u), y2 = __uint_as_float(yy.y << 16), y3 = __uint_as_float(yy.y & 0xffff0000u);
;           *(uint2*)(ea.outb + a_off(row, 512 + col, 32)) = uint2{pk2(y0 * sigmoid_(v[0] + b4[0]), y1 * sigmoid_(v[1] + b4[1])), pk2(y2 * sigmoid_(v[2] + b4[2]), y3 * sigmoid_(v[3] + b4[3]))};
	v_lshlrev_b32_e32 v34, 16, v28
	v_add_f32_e32 v20, v20, v24
	v_add_f32_e32 v21, v21, v25
	v_add_f32_e32 v22, v22, v26
	v_add_f32_e32 v23, v23, v27
	v_mul_f32_e32 v20, 0xbfb8aa3b, v20
	v_mul_f32_e32 v21, 0xbfb8aa3b, v21
	v_mul_f32_e32 v22, 0xbfb8aa3b, v22
	v_mul_f32_e32 v23, 0xbfb8aa3b, v23
	v_exp_f32_e32 v20, v20
	v_exp_f32_e32 v21, v21
	v_exp_f32_e32 v22, v22
	v_exp_f32_e32 v23, v23
	v_add_f32_e32 v20, 1.0, v20
	v_add_f32_e32 v21, 1.0, v21
	v_add_f32_e32 v22, 1.0, v22
	v_add_f32_e32 v23, 1.0, v23
	v_rcp_f32_e32 v20, v20
	v_rcp_f32_e32 v21, v21
	v_rcp_f32_e32 v22, v22
	v_rcp_f32_e32 v23, v23
	v_and_b32_e32 v35, 0xffff0000, v28
	v_lshlrev_b32_e32 v24, 16, v29
	v_and_b32_e32 v25, 0xffff0000, v29
	v_pk_mul_f32 v[20:21], v[20:21], v[34:35]
	v_pk_mul_f32 v[22:23], v[22:23], v[24:25]
	v_cvt_pk_bf16_f32 v20, v20, v21
	v_cvt_pk_bf16_f32 v21, v22, v23
	v_mov_b32_e32 v250, v30
	v_mov_b32_e32 v251, v31
	v_mov_b32_e32 v252, v20
	v_mov_b32_e32 v253, v21
	global_load_dwordx2 v[24:25], v[32:33], off
	s_nop 0
	global_load_dwordx4 v[20:23], v[124:125], off offset:192
	global_store_dwordx2 v[250:251], v[252:253], off
	v_lshl_add_u64 v[28:29], v[116:117], 0, v[150:151]
	v_lshl_add_u64 v[26:27], v[160:161], 0, v[152:153]
	s_waitcnt vmcnt(1)
	v_lshlrev_b32_e32 v30, 16, v24
	v_add_f32_e32 v12, v12, v20
	v_add_f32_e32 v13, v13, v21
	v_add_f32_e32 v14, v14, v22
	v_add_f32_e32 v15, v15, v23
	v_mul_f32_e32 v12, 0xbfb8aa3b, v12
	v_mul_f32_e32 v13, 0xbfb8aa3b, v13
	v_mul_f32_e32 v14, 0xbfb8aa3b, v14
	v_mul_f32_e32 v15, 0xbfb8aa3b, v15
	v_exp_f32_e32 v12, v12
	v_exp_f32_e32 v13, v13
	v_exp_f32_e32 v14, v14
	v_exp_f32_e32 v15, v15
	v_add_f32_e32 v12, 1.0, v12
	v_add_f32_e32 v13, 1.0, v13
	v_add_f32_e32 v14, 1.0, v14
	v_add_f32_e32 v15, 1.0, v15
	v_rcp_f32_e32 v12, v12
	v_rcp_f32_e32 v13, v13
	v_rcp_f32_e32 v14, v14
	v_rcp_f32_e32 v15, v15
	v_and_b32_e32 v31, 0xffff0000, v24
	v_lshlrev_b32_e32 v20, 16, v25
	v_and_b32_e32 v21, 0xffff0000, v25
	v_pk_mul_f32 v[12:13], v[12:13], v[30:31]
	v_pk_mul_f32 v[14:15], v[14:15], v[20:21]
	v_cvt_pk_bf16_f32 v12, v12, v13
	v_cvt_pk_bf16_f32 v13, v14, v15
	v_mov_b32_e32 v250, v28
	v_mov_b32_e32 v251, v29
	v_mov_b32_e32 v252, v12
	v_mov_b32_e32 v253, v13
	global_load_dwordx2 v[20:21], v[26:27], off
	s_nop 0
	global_load_dwordx4 v[12:15], v[154:155], off
	global_store_dwordx2 v[250:251], v[252:253], off
	v_lshl_add_u64 v[22:23], v[158:159], 0, v[152:153]
	v_lshl_add_u64 v[24:25], v[156:157], 0, v[152:153]
	s_waitcnt vmcnt(1)
	v_lshlrev_b32_e32 v26, 16, v20
	v_add_f32_e32 v12, v16, v12
	v_add_f32_e32 v13, v17, v13
	v_add_f32_e32 v14, v18, v14
	v_add_f32_e32 v15, v19, v15
	v_mul_f32_e32 v12, 0xbfb8aa3b, v12
	v_mul_f32_e32 v13, 0xbfb8aa3b, v13
	v_mul_f32_e32 v14, 0xbfb8aa3b, v14
	v_mul_f32_e32 v15, 0xbfb8aa3b, v15
	v_exp_f32_e32 v12, v12
	v_exp_f32_e32 v13, v13
	v_exp_f32_e32 v14, v14
	v_exp_f32_e32 v15, v15
	v_add_f32_e32 v12, 1.0, v12
	v_add_f32_e32 v13, 1.0, v13
	v_add_f32_e32 v14, 1.0, v14
	v_add_f32_e32 v15, 1.0, v15
	v_rcp_f32_e32 v12, v12
	v_rcp_f32_e32 v13, v13
	v_rcp_f32_e32 v14, v14
	v_rcp_f32_e32 v15, v15
	v_and_b32_e32 v27, 0xffff0000, v20
	v_lshlrev_b32_e32 v16, 16, v21
	v_and_b32_e32 v17, 0xffff0000, v21
	v_pk_mul_f32 v[12:13], v[12:13], v[26:27]
	v_pk_mul_f32 v[14:15], v[14:15], v[16:17]
	v_cvt_pk_bf16_f32 v12, v12, v13
	v_cvt_pk_bf16_f32 v13, v14, v15
	v_mov_b32_e32 v250, v22
	v_mov_b32_e32 v251, v23
	v_mov_b32_e32 v252, v12
	v_mov_b32_e32 v253, v13
	global_load_dwordx2 v[16:17], v[24:25], off
	s_nop 0
	global_load_dwordx4 v[12:15], v[124:125], off offset:64
	global_store_dwordx2 v[250:251], v[252:253], off
	v_lshl_add_u64 v[18:19], v[162:163], 0, v[152:153]
	v_lshl_add_u64 v[20:21], v[126:127], 0, v[152:153]
	s_waitcnt vmcnt(1)
	v_lshlrev_b32_e32 v22, 16, v16
	v_add_f32_e32 v8, v8, v12
	v_add_f32_e32 v9, v9, v13
	v_add_f32_e32 v10, v10, v14
	v_add_f32_e32 v11, v11, v15
	v_mul_f32_e32 v8, 0xbfb8aa3b, v8
	v_mul_f32_e32 v9, 0xbfb8aa3b, v9
	v_mul_f32_e32 v10, 0xbfb8aa3b, v10
	v_mul_f32_e32 v11, 0xbfb8aa3b, v11
	v_exp_f32_e32 v8, v8
	v_exp_f32_e32 v9, v9
	v_exp_f32_e32 v10, v10
	v_exp_f32_e32 v11, v11
	v_add_f32_e32 v8, 1.0, v8
	v_add_f32_e32 v9, 1.0, v9
	v_add_f32_e32 v10, 1.0, v10
	v_add_f32_e32 v11, 1.0, v11
	v_rcp_f32_e32 v8, v8
	v_rcp_f32_e32 v9, v9
	v_rcp_f32_e32 v10, v10
	v_rcp_f32_e32 v11, v11
	v_and_b32_e32 v23, 0xffff0000, v16
	v_lshlrev_b32_e32 v12, 16, v17
	v_and_b32_e32 v13, 0xffff0000, v17
	v_pk_mul_f32 v[8:9], v[8:9], v[22:23]
	v_pk_mul_f32 v[10:11], v[10:11], v[12:13]
	v_cvt_pk_bf16_f32 v8, v8, v9
	v_cvt_pk_bf16_f32 v9, v10, v11
	v_mov_b32_e32 v250, v18
	v_mov_b32_e32 v251, v19
	v_mov_b32_e32 v252, v8
	v_mov_b32_e32 v253, v9
	global_load_dwordx2 v[12:13], v[20:21], off
	s_nop 0
	global_load_dwordx4 v[8:11], v[124:125], off offset:128
	global_store_dwordx2 v[250:251], v[252:253], off
	v_lshl_add_u64 v[14:15], v[122:123], 0, v[152:153]
	v_lshl_add_u64 v[16:17], v[120:121], 0, v[152:153]
	s_waitcnt vmcnt(1)
	v_lshlrev_b32_e32 v18, 16, v12
	v_add_f32_e32 v4, v4, v8
	v_add_f32_e32 v5, v5, v9
	v_add_f32_e32 v6, v6, v10
	v_add_f32_e32 v7, v7, v11
	v_mul_f32_e32 v4, 0xbfb8aa3b, v4
	v_mul_f32_e32 v5, 0xbfb8aa3b, v5
	v_mul_f32_e32 v6, 0xbfb8aa3b, v6
	v_mul_f32_e32 v7, 0xbfb8aa3b, v7
	v_exp_f32_e32 v4, v4
	v_exp_f32_e32 v5, v5
	v_exp_f32_e32 v6, v6
	v_exp_f32_e32 v7, v7
	v_add_f32_e32 v4, 1.0, v4
	v_add_f32_e32 v5, 1.0, v5
	v_add_f32_e32 v6, 1.0, v6
	v_add_f32_e32 v7, 1.0, v7
	v_rcp_f32_e32 v4, v4
	v_rcp_f32_e32 v5, v5
	v_rcp_f32_e32 v6, v6
	v_rcp_f32_e32 v7, v7
	v_and_b32_e32 v19, 0xffff0000, v12
	v_lshlrev_b32_e32 v8, 16, v13
	v_and_b32_e32 v9, 0xffff0000, v13
	v_pk_mul_f32 v[4:5], v[4:5], v[18:19]
	v_pk_mul_f32 v[6:7], v[6:7], v[8:9]
	v_cvt_pk_bf16_f32 v4, v4, v5
	v_cvt_pk_bf16_f32 v5, v6, v7
	v_mov_b32_e32 v250, v14
	v_mov_b32_e32 v251, v15
	v_mov_b32_e32 v252, v4
	v_mov_b32_e32 v253, v5
	global_load_dwordx2 v[8:9], v[16:17], off
	s_nop 0
	global_load_dwordx4 v[4:7], v[124:125], off offset:192
	global_store_dwordx2 v[250:251], v[252:253], off
	v_lshl_add_u64 v[10:11], v[116:117], 0, v[152:153]
	s_waitcnt vmcnt(1)
	v_lshlrev_b32_e32 v12, 16, v8
	v_add_f32_e32 v0, v0, v4
	v_add_f32_e32 v1, v1, v5
	v_add_f32_e32 v2, v2, v6
	v_add_f32_e32 v3, v3, v7
	v_mul_f32_e32 v0, 0xbfb8aa3b, v0
	v_mul_f32_e32 v1, 0xbfb8aa3b, v1
	v_mul_f32_e32 v2, 0xbfb8aa3b, v2
	v_mul_f32_e32 v3, 0xbfb8aa3b, v3
	v_exp_f32_e32 v0, v0
	v_exp_f32_e32 v1, v1
	v_exp_f32_e32 v2, v2
	v_exp_f32_e32 v3, v3
	v_add_f32_e32 v0, 1.0, v0
	v_add_f32_e32 v1, 1.0, v1
	v_add_f32_e32 v2, 1.0, v2
	v_add_f32_e32 v3, 1.0, v3
	v_rcp_f32_e32 v0, v0
	v_rcp_f32_e32 v1, v1
	v_rcp_f32_e32 v2, v2
	v_rcp_f32_e32 v3, v3
	v_and_b32_e32 v13, 0xffff0000, v8
	v_lshlrev_b32_e32 v4, 16, v9
	v_and_b32_e32 v5, 0xffff0000, v9
	v_pk_mul_f32 v[0:1], v[0:1], v[12:13]
	v_pk_mul_f32 v[2:3], v[2:3], v[4:5]
	v_cvt_pk_bf16_f32 v0, v0, v1
	v_cvt_pk_bf16_f32 v1, v2, v3
	global_store_dwordx2 v[10:11], v[0:1], off
	s_mov_b32 s50, s29
	s_mov_b32 s35, s33

; __device__ __forceinline__ u16 f2bf(float x) { unsigned u = __float_as_uint(x); u += 0x7fffu + ((u >> 16) & 1u); return (u16)(u >> 16); }
; __device__ __forceinline__ size_t a_off(int row, int col, int nks) { return ((size_t)((row >> 8) * nks + (col >> 5)) << 13) + ((row & 255) << 5) + swzc(row, col & 31); }
; template <int MODE>
; __device__ __forceinline__ void norm_phase(const Params& p, const float* src, const float* w, const float* modl, int sh_off, int sc_off,
;                            char* smem, int bid, int nblk) {
;     ...
;     float ss = 0.f;
; #pragma unroll
;     for (int i = 0; i < 4; ++i) ss += v[i][0] * v[i][0] + v[i][1] * v[i][1] + v[i][2] * v[i][2] + v[i][3] * v[i][3];
; #pragma unroll
;     for (int o = 32; o >= 1; o >>= 1) ss += __shfl_xor(ss, o);
;     const float rstd = rsqrtf(ss * (1.f / 1024.f) + 1e-6f);
;     const int b = row >> 13;
;     float dots[8];
;     if (MODE == 1) { for (int j = 0; j < 8; ++j) dots[j] = 0.f; }
; #pragma unroll
;     for (int i = 0; i < 4; ++i) {
;       const int c0 = i * 256 + lane * 4;
;       f32x4 ww = *(const f32x4*)(w + c0);
;       f32x4 y;
;       if (MODE == 2) {
; #pragma unroll
;         for (int e = 0; e < 4; ++e) y[e] = v[i][e] * rstd * ww[e];
;         *(f32x4*)(p.out + (size_t)row * 1024 + c0) = y;
;       } else {
;         f32x4 sc = *(const f32x4*)(modl + (size_t)b * 6144 + sc_off + c0);
;         f32x4 sh = *(const f32x4*)(modl + (size_t)b * 6144 + sh_off + c0);
; #pragma unroll
;         for (int e = 0; e < 4; ++e) y[e] = v[i][e] * rstd * ww[e] * (1.f + sc[e]) + sh[e];
;         uint2 pk; pk.x = (unsigned)f2bf(y[0]) | ((unsigned)f2bf(y[1]) << 16); pk.y = (unsigned)f2bf(y[2]) | ((unsigned)f2bf(y[3]) << 16);
;         *(uint2*)(hn + a_off(row, c0, 32)) = pk;
.LBB0_1646:
	s_or_b64 exec, exec, s[0:1]
	v_ashrrev_i32_e32 v34, 13, v33
	v_mul_i32_i24_e32 v66, 0x1800, v34
	v_ashrrev_i32_e32 v67, 31, v66
	v_lshl_add_u64 v[68:69], v[66:67], 2, s[6:7]
	v_lshl_add_u64 v[66:67], v[68:69], 0, s[8:9]
	global_load_dwordx4 v[88:91], v[38:39], off
	v_lshl_add_u64 v[92:93], v[66:67], 0, v[50:51]
	global_load_dwordx4 v[92:95], v[92:93], off
	v_lshl_add_u64 v[68:69], v[68:69], 0, v[50:51]
	global_load_dwordx4 v[96:99], v[68:69], off
	s_waitcnt vmcnt(0)
	v_pk_mul_f32 v[102:103], v[28:29], v[28:29]
	v_pk_mul_f32 v[104:105], v[24:25], v[24:25]
	v_pk_mul_f32 v[70:71], v[30:31], v[30:31]
	v_pk_mul_f32 v[100:101], v[26:27], v[26:27]
	v_mov_b32_e32 v106, v102
	v_mov_b32_e32 v107, v104
	v_mov_b32_e32 v104, v103
	v_pk_add_f32 v[102:103], v[106:107], v[104:105]
	v_mov_b32_e32 v104, v70
	v_mov_b32_e32 v105, v100
	v_pk_add_f32 v[102:103], v[104:105], v[102:103]
	v_mov_b32_e32 v100, v71
	v_pk_add_f32 v[70:71], v[100:101], v[102:103]
	v_mov_b32_e32 v102, v17
	v_mov_b32_e32 v103, v21
	v_mov_b32_e32 v100, v16
	v_mov_b32_e32 v101, v20
	v_pk_mul_f32 v[102:103], v[102:103], v[102:103]
	v_add_f32_e32 v34, v70, v71
	v_pk_fma_f32 v[100:101], v[100:101], v[100:101], v[102:103]
	v_mov_b32_e32 v102, v18
	v_mov_b32_e32 v103, v22
	v_pk_fma_f32 v[100:101], v[102:103], v[102:103], v[100:101]
	v_mov_b32_e32 v102, v19
	v_mov_b32_e32 v103, v23
	v_pk_fma_f32 v[100:101], v[102:103], v[102:103], v[100:101]
	v_and_b32_e32 v61, 24, v83
	v_add_f32_e32 v34, v101, v34
	v_add_f32_e32 v34, v100, v34
	ds_bpermute_b32 v49, v72, v34
	v_mov_b32_e32 v101, v30
	v_mov_b32_e32 v30, v29
	v_and_b32_e32 v57, 0x1fe0, v84
	v_sub_u32_e32 v61, 0, v61
	s_waitcnt lgkmcnt(0)
	v_add_f32_e32 v34, v34, v49
	ds_bpermute_b32 v49, v73, v34
	v_mov_b32_e32 v100, v28
	v_ashrrev_i32_e32 v53, 3, v33
	v_and_b32_e32 v53, 0xffffffe0, v53
	v_or_b32_e32 v28, v53, v78
	s_waitcnt lgkmcnt(0)
	v_add_f32_e32 v34, v34, v49
	ds_bpermute_b32 v49, v74, v34
	v_mov_b32_e32 v71, v35
	s_waitcnt lgkmcnt(0)
	v_add_f32_e32 v34, v34, v49
	ds_bpermute_b32 v49, v75, v34
	s_waitcnt lgkmcnt(0)
	v_add_f32_e32 v29, v34, v49
	ds_bpermute_b32 v49, v76, v29
	v_lshlrev_b32_e32 v34, 1, v57
	v_xor_b32_e32 v57, v32, v61
	v_and_or_b32 v57, v57, 24, v79
	v_lshlrev_b32_e32 v70, 1, v57
	s_waitcnt lgkmcnt(0)
	v_add_f32_e32 v49, v29, v49
	ds_bpermute_b32 v61, v77, v49
	v_ashrrev_i32_e32 v29, 31, v28
	v_lshlrev_b64 v[28:29], 14, v[28:29]
	v_lshl_add_u64 v[28:29], s[62:63], 0, v[28:29]
	v_lshl_add_u64 v[28:29], v[28:29], 0, v[34:35]
	s_waitcnt lgkmcnt(0)
	v_add_f32_e32 v49, v49, v61
	v_fmamk_f32 v49, v49, 0x3a800000, v85
	v_mul_f32_e32 v57, 0x4b800000, v49
	v_cmp_gt_f32_e64 s[0:1], s18, v49
	v_lshl_add_u64 v[28:29], v[28:29], 0, v[70:71]
	v_mov_b32_e32 v105, v90
	v_cndmask_b32_e64 v49, v49, v57, s[0:1]
	v_rsq_f32_e32 v49, v49
	v_mov_b32_e32 v90, v89
	v_mov_b32_e32 v104, v88
	v_mul_f32_e32 v57, 0x45800000, v49
	v_cndmask_b32_e64 v102, v49, v57, s[0:1]
	v_pk_mul_f32 v[30:31], v[30:31], v[102:103] op_sel_hi:[1,0]
	v_pk_mul_f32 v[100:101], v[100:101], v[102:103] op_sel_hi:[1,0]
	v_pk_mul_f32 v[30:31], v[90:91], v[30:31]
	v_mov_b32_e32 v90, v92
	v_mov_b32_e32 v91, v94
	v_pk_mul_f32 v[88:89], v[104:105], v[100:101]
	v_mov_b32_e32 v100, v96
	v_mov_b32_e32 v101, v98
	v_pk_add_f32 v[90:91], v[90:91], 1.0 op_sel_hi:[1,0]
	v_mov_b32_e32 v94, v93
	v_pk_fma_f32 v[88:89], v[90:91], v[88:89], v[100:101]
	v_pk_add_f32 v[90:91], v[94:95], 1.0 op_sel_hi:[1,0]
	v_mov_b32_e32 v98, v97
	v_pk_fma_f32 v[30:31], v[90:91], v[30:31], v[98:99]
	v_and_b32_sdwa v49, v89, v86 dst_sel:DWORD dst_unused:UNUSED_PAD src0_sel:WORD_1 src1_sel:DWORD
	v_and_b32_sdwa v61, v31, v86 dst_sel:DWORD dst_unused:UNUSED_PAD src0_sel:WORD_1 src1_sel:DWORD
	v_and_b32_sdwa v65, v30, v86 dst_sel:DWORD dst_unused:UNUSED_PAD src0_sel:WORD_1 src1_sel:DWORD
	v_and_b32_sdwa v57, v88, v86 dst_sel:DWORD dst_unused:UNUSED_PAD src0_sel:WORD_1 src1_sel:DWORD
	v_add3_u32 v31, v31, v61, s19
	v_add3_u32 v30, v30, v65, s19
	v_add3_u32 v57, v88, v57, s19
	v_add3_u32 v49, v89, v49, s19
	v_and_b32_e32 v31, 0xffff0000, v31
	v_and_b32_e32 v30, 0xffff0000, v30
	v_or_b32_sdwa v31, v31, v49 dst_sel:DWORD dst_unused:UNUSED_PAD src0_sel:DWORD src1_sel:WORD_1
	v_or_b32_sdwa v30, v30, v57 dst_sel:DWORD dst_unused:UNUSED_PAD src0_sel:DWORD src1_sel:WORD_1
	v_mov_b32_e32 v250, v28
	v_mov_b32_e32 v251, v29
	v_mov_b32_e32 v252, v30
	v_mov_b32_e32 v253, v31
	global_load_dwordx4 v[28:31], v[40:41], off
	v_lshl_add_u64 v[96:97], v[66:67], 0, v[54:55]
	global_load_dwordx4 v[88:91], v[96:97], off
	global_load_dwordx4 v[92:95], v[68:69], off offset:1024
	global_store_dwordx2 v[250:251], v[252:253], off
	v_mov_b32_e32 v97, v26
	v_mov_b32_e32 v26, v25
	v_mov_b32_e32 v96, v24
	v_pk_mul_f32 v[26:27], v[26:27], v[102:103] op_sel_hi:[1,0]
	v_or_b32_e32 v24, v53, v80
	v_pk_mul_f32 v[96:97], v[96:97], v[102:103] op_sel_hi:[1,0]
	v_ashrrev_i32_e32 v25, 31, v24
	v_lshlrev_b64 v[24:25], 14, v[24:25]
	v_lshl_add_u64 v[24:25], s[62:63], 0, v[24:25]
	v_lshl_add_u64 v[24:25], v[24:25], 0, v[34:35]
	v_lshl_add_u64 v[24:25], v[24:25], 0, v[70:71]
	s_waitcnt vmcnt(3)
	v_mov_b32_e32 v99, v30
	s_waitcnt vmcnt(2)
	v_mov_b32_e32 v101, v90
	v_mov_b32_e32 v30, v29
	v_mov_b32_e32 v90, v89
	v_mov_b32_e32 v98, v28
	v_mov_b32_e32 v100, v88
	s_waitcnt vmcnt(1)
; __device__ __forceinline__ u16 f2bf(float x) { unsigned u = __float_as_uint(x); u += 0x7fffu + ((u >> 16) & 1u); return (u16)(u >> 16); }
; __device__ __forceinline__ size_t a_off(int row, int col, int nks) { return ((size_t)((row >> 8) * nks + (col >> 5)) << 13) + ((row & 255) << 5) + swzc(row, col & 31); }
; template <int MODE>
; __device__ __forceinline__ void norm_phase(const Params& p, const float* src, const float* w, const float* modl, int sh_off, int sc_off,
;                            char* smem, int bid, int nblk) {
;     ...
;       f32x4 ww = *(const f32x4*)(w + c0);
;       f32x4 y;
;       if (MODE == 2) {
; #pragma unroll
;         for (int e = 0; e < 4; ++e) y[e] = v[i][e] * rstd * ww[e];
;         *(f32x4*)(p.out + (size_t)row * 1024 + c0) = y;
;       } else {
;         f32x4 sc = *(const f32x4*)(modl + (size_t)b * 6144 + sc_off + c0);
;         f32x4 sh = *(const f32x4*)(modl + (size_t)b * 6144 + sh_off + c0);
; #pragma unroll
;         for (int e = 0; e < 4; ++e) y[e] = v[i][e] * rstd * ww[e] * (1.f + sc[e]) + sh[e];
;         uint2 pk; pk.x = (unsigned)f2bf(y[0]) | ((unsigned)f2bf(y[1]) << 16); pk.y = (unsigned)f2bf(y[2]) | ((unsigned)f2bf(y[3]) << 16);
;         *(uint2*)(hn + a_off(row, c0, 32)) = pk;
	v_mov_b32_e32 v105, v94
	v_mov_b32_e32 v94, v93
	v_pk_mul_f32 v[26:27], v[30:31], v[26:27]
	v_pk_add_f32 v[30:31], v[90:91], 1.0 op_sel_hi:[1,0]
	v_mov_b32_e32 v104, v92
	v_pk_mul_f32 v[28:29], v[98:99], v[96:97]
	v_pk_add_f32 v[88:89], v[100:101], 1.0 op_sel_hi:[1,0]
	v_pk_fma_f32 v[26:27], v[30:31], v[26:27], v[94:95]
	v_pk_fma_f32 v[28:29], v[88:89], v[28:29], v[104:105]
	v_and_b32_sdwa v49, v27, v86 dst_sel:DWORD dst_unused:UNUSED_PAD src0_sel:WORD_1 src1_sel:DWORD
	v_and_b32_sdwa v57, v26, v86 dst_sel:DWORD dst_unused:UNUSED_PAD src0_sel:WORD_1 src1_sel:DWORD
	v_and_b32_sdwa v30, v29, v86 dst_sel:DWORD dst_unused:UNUSED_PAD src0_sel:WORD_1 src1_sel:DWORD
	v_and_b32_sdwa v31, v28, v86 dst_sel:DWORD dst_unused:UNUSED_PAD src0_sel:WORD_1 src1_sel:DWORD
	v_add3_u32 v27, v27, v49, s19
	v_add3_u32 v26, v26, v57, s19
	v_add3_u32 v28, v28, v31, s19
	v_add3_u32 v29, v29, v30, s19
	v_and_b32_e32 v27, 0xffff0000, v27
	v_and_b32_e32 v26, 0xffff0000, v26
	v_or_b32_sdwa v27, v27, v29 dst_sel:DWORD dst_unused:UNUSED_PAD src0_sel:DWORD src1_sel:WORD_1
	v_or_b32_sdwa v26, v26, v28 dst_sel:DWORD dst_unused:UNUSED_PAD src0_sel:DWORD src1_sel:WORD_1
	v_mov_b32_e32 v250, v24
	v_mov_b32_e32 v251, v25
	v_mov_b32_e32 v252, v26
	v_mov_b32_e32 v253, v27
	global_load_dwordx4 v[24:27], v[42:43], off
	v_lshl_add_u64 v[92:93], v[66:67], 0, v[58:59]
	global_load_dwordx4 v[28:31], v[92:93], off
	global_load_dwordx4 v[88:91], v[68:69], off offset:2048
	global_store_dwordx2 v[250:251], v[252:253], off
	v_mov_b32_e32 v93, v22
	v_mov_b32_e32 v22, v21
	v_mov_b32_e32 v92, v20
	v_pk_mul_f32 v[22:23], v[22:23], v[102:103] op_sel_hi:[1,0]
	v_or_b32_e32 v20, v53, v81
	v_pk_mul_f32 v[92:93], v[92:93], v[102:103] op_sel_hi:[1,0]
	v_ashrrev_i32_e32 v21, 31, v20
	v_lshlrev_b64 v[20:21], 14, v[20:21]
	v_lshl_add_u64 v[20:21], s[62:63], 0, v[20:21]
	v_lshl_add_u64 v[20:21], v[20:21], 0, v[34:35]
	v_lshl_add_u64 v[20:21], v[20:21], 0, v[70:71]
	v_lshl_add_u64 v[66:67], v[66:67], 0, v[62:63]
	s_waitcnt vmcnt(3)
	v_mov_b32_e32 v95, v26
	s_waitcnt vmcnt(2)
	v_mov_b32_e32 v97, v30
	v_mov_b32_e32 v26, v25
	v_mov_b32_e32 v30, v29
	v_mov_b32_e32 v94, v24
	v_mov_b32_e32 v96, v28
	s_waitcnt vmcnt(1)
	v_mov_b32_e32 v99, v90
	v_mov_b32_e32 v90, v89
	v_pk_mul_f32 v[22:23], v[22:23], v[26:27]
	v_pk_add_f32 v[26:27], v[30:31], 1.0 op_sel_hi:[1,0]
	v_mov_b32_e32 v98, v88
	v_pk_mul_f32 v[24:25], v[92:93], v[94:95]
	v_pk_add_f32 v[28:29], v[96:97], 1.0 op_sel_hi:[1,0]
	v_pk_fma_f32 v[22:23], v[22:23], v[26:27], v[90:91]
	v_pk_fma_f32 v[24:25], v[24:25], v[28:29], v[98:99]
	v_and_b32_sdwa v28, v23, v86 dst_sel:DWORD dst_unused:UNUSED_PAD src0_sel:WORD_1 src1_sel:DWORD
	v_and_b32_sdwa v29, v22, v86 dst_sel:DWORD dst_unused:UNUSED_PAD src0_sel:WORD_1 src1_sel:DWORD
	v_and_b32_sdwa v26, v25, v86 dst_sel:DWORD dst_unused:UNUSED_PAD src0_sel:WORD_1 src1_sel:DWORD
	v_and_b32_sdwa v27, v24, v86 dst_sel:DWORD dst_unused:UNUSED_PAD src0_sel:WORD_1 src1_sel:DWORD
	v_add3_u32 v23, v23, v28, s19
	v_add3_u32 v22, v22, v29, s19
	v_add3_u32 v24, v24, v27, s19
	v_add3_u32 v25, v25, v26, s19
	v_and_b32_e32 v23, 0xffff0000, v23
	v_and_b32_e32 v22, 0xffff0000, v22
	v_or_b32_sdwa v23, v23, v25 dst_sel:DWORD dst_unused:UNUSED_PAD src0_sel:DWORD src1_sel:WORD_1
	v_or_b32_sdwa v22, v22, v24 dst_sel:DWORD dst_unused:UNUSED_PAD src0_sel:DWORD src1_sel:WORD_1
	v_mov_b32_e32 v250, v20
	v_mov_b32_e32 v251, v21
	v_mov_b32_e32 v252, v22
	v_mov_b32_e32 v253, v23
	global_load_dwordx4 v[20:23], v[44:45], off
	s_nop 0
	global_load_dwordx4 v[24:27], v[66:67], off
	global_load_dwordx4 v[28:31], v[68:69], off offset:3072
	global_store_dwordx2 v[250:251], v[252:253], off
	v_mov_b32_e32 v66, v16
	v_or_b32_e32 v16, v53, v82
	v_mov_b32_e32 v67, v18
	v_mov_b32_e32 v18, v17
	v_ashrrev_i32_e32 v17, 31, v16
	v_lshlrev_b64 v[16:17], 14, v[16:17]
	v_lshl_add_u64 v[16:17], s[62:63], 0, v[16:17]
	v_lshl_add_u64 v[16:17], v[16:17], 0, v[34:35]
	v_lshl_add_u64 v[16:17], v[16:17], 0, v[70:71]
	v_pk_mul_f32 v[18:19], v[18:19], v[102:103] op_sel_hi:[1,0]
	v_pk_mul_f32 v[66:67], v[66:67], v[102:103] op_sel_hi:[1,0]
	s_waitcnt vmcnt(2)
	v_mov_b32_e32 v71, v26
	v_mov_b32_e32 v69, v22
	v_mov_b32_e32 v22, v21
	v_mov_b32_e32 v26, v25
	v_mov_b32_e32 v68, v20
	v_mov_b32_e32 v70, v24
	s_waitcnt vmcnt(1)
	v_mov_b32_e32 v89, v30
	v_mov_b32_e32 v30, v29
	v_pk_mul_f32 v[18:19], v[18:19], v[22:23]
	v_pk_add_f32 v[22:23], v[26:27], 1.0 op_sel_hi:[1,0]
	v_mov_b32_e32 v88, v28
	v_pk_mul_f32 v[20:21], v[66:67], v[68:69]
	v_pk_add_f32 v[24:25], v[70:71], 1.0 op_sel_hi:[1,0]
	v_pk_fma_f32 v[18:19], v[18:19], v[22:23], v[30:31]
	v_pk_fma_f32 v[20:21], v[20:21], v[24:25], v[88:89]
	v_and_b32_sdwa v24, v19, v86 dst_sel:DWORD dst_unused:UNUSED_PAD src0_sel:WORD_1 src1_sel:DWORD
	v_and_b32_sdwa v25, v18, v86 dst_sel:DWORD dst_unused:UNUSED_PAD src0_sel:WORD_1 src1_sel:DWORD
	v_and_b32_sdwa v22, v21, v86 dst_sel:DWORD dst_unused:UNUSED_PAD src0_sel:WORD_1 src1_sel:DWORD
	v_and_b32_sdwa v23, v20, v86 dst_sel:DWORD dst_unused:UNUSED_PAD src0_sel:WORD_1 src1_sel:DWORD
	v_add3_u32 v19, v19, v24, s19
	v_add3_u32 v18, v18, v25, s19
	v_add3_u32 v20, v20, v23, s19
	v_add3_u32 v21, v21, v22, s19
	v_and_b32_e32 v19, 0xffff0000, v19
	v_and_b32_e32 v18, 0xffff0000, v18
	v_or_b32_sdwa v19, v19, v21 dst_sel:DWORD dst_unused:UNUSED_PAD src0_sel:DWORD src1_sel:WORD_1
	v_or_b32_sdwa v18, v18, v20 dst_sel:DWORD dst_unused:UNUSED_PAD src0_sel:DWORD src1_sel:WORD_1
	global_store_dwordx2 v[16:17], v[18:19], off
	s_and_saveexec_b64 s[0:1], vcc
	s_cbranch_execz .LBB0_1637
; __device__ __forceinline__ u16 f2bf(float x) { unsigned u = __float_as_uint(x); u += 0x7fffu + ((u >> 16) & 1u); return (u16)(u >> 16); }
; __device__ __forceinline__ size_t a_off(int row, int col, int nks) { return ((size_t)((row >> 8) * nks + (col >> 5)) << 13) + ((row & 255) << 5) + swzc(row, col & 31); }
; template <int MODE>
; __device__ __forceinline__ void norm_phase(const Params& p, const float* src, const float* w, const float* modl, int sh_off, int sc_off,
;                            char* smem, int bid, int nblk) {
;     ...
;     float ss = 0.f;
; #pragma unroll
;     for (int i = 0; i < 4; ++i) ss += v[i][0] * v[i][0] + v[i][1] * v[i][1] + v[i][2] * v[i][2] + v[i][3] * v[i][3];
; #pragma unroll
;     for (int o = 32; o >= 1; o >>= 1) ss += __shfl_xor(ss, o);
;     const float rstd = rsqrtf(ss * (1.f / 1024.f) + 1e-6f);
;     const int b = row >> 13;
;     float dots[8];
;     if (MODE == 1) { for (int j = 0; j < 8; ++j) dots[j] = 0.f; }
; #pragma unroll
;     for (int i = 0; i < 4; ++i) {
;       const int c0 = i * 256 + lane * 4;
;       f32x4 ww = *(const f32x4*)(w + c0);
;       f32x4 y;
;       if (MODE == 2) {
; #pragma unroll
;         for (int e = 0; e < 4; ++e) y[e] = v[i][e] * rstd * ww[e];
;         *(f32x4*)(p.out + (size_t)row * 1024 + c0) = y;
;       } else {
;         f32x4 sc = *(const f32x4*)(modl + (size_t)b * 6144 + sc_off + c0);
;         f32x4 sh = *(const f32x4*)(modl + (size_t)b * 6144 + sh_off + c0);
; #pragma unroll
;         for (int e = 0; e < 4; ++e) y[e] = v[i][e] * rstd * ww[e] * (1.f + sc[e]) + sh[e];
;         uint2 pk; pk.x = (unsigned)f2bf(y[0]) | ((unsigned)f2bf(y[1]) << 16); pk.y = (unsigned)f2bf(y[2]) | ((unsigned)f2bf(y[3]) << 16);
;         *(uint2*)(hn + a_off(row, c0, 32)) = pk;
	v_ashrrev_i32_e32 v16, 13, v64
	v_mul_i32_i24_e32 v16, 0x1800, v16
	v_ashrrev_i32_e32 v17, 31, v16
	v_lshl_add_u64 v[18:19], v[16:17], 2, s[6:7]
	v_lshl_add_u64 v[16:17], v[18:19], 0, s[8:9]
	v_mov_b32_e32 v49, v35
	global_load_dwordx4 v[22:25], v[38:39], off
	v_lshl_add_u64 v[26:27], v[16:17], 0, v[48:49]
	global_load_dwordx4 v[26:29], v[26:27], off
	v_lshl_add_u64 v[18:19], v[18:19], 0, v[48:49]
	global_load_dwordx4 v[66:69], v[18:19], off
	v_pk_mul_f32 v[70:71], v[8:9], v[8:9]
	v_pk_mul_f32 v[88:89], v[12:13], v[12:13]
	v_pk_mul_f32 v[20:21], v[14:15], v[14:15]
	v_pk_mul_f32 v[30:31], v[10:11], v[10:11]
	v_mov_b32_e32 v90, v88
	v_mov_b32_e32 v91, v70
	v_mov_b32_e32 v70, v89
	v_pk_add_f32 v[70:71], v[90:91], v[70:71]
	v_mov_b32_e32 v88, v20
	v_mov_b32_e32 v89, v30
	v_pk_add_f32 v[70:71], v[88:89], v[70:71]
	v_mov_b32_e32 v30, v21
	v_pk_add_f32 v[20:21], v[30:31], v[70:71]
	v_mov_b32_e32 v70, v5
	v_mov_b32_e32 v71, v1
	v_mov_b32_e32 v30, v4
	v_mov_b32_e32 v31, v0
	v_pk_mul_f32 v[70:71], v[70:71], v[70:71]
	v_add_f32_e32 v20, v20, v21
	v_pk_fma_f32 v[30:31], v[30:31], v[30:31], v[70:71]
	v_mov_b32_e32 v70, v6
	v_mov_b32_e32 v71, v2
	v_pk_fma_f32 v[30:31], v[70:71], v[70:71], v[30:31]
	v_mov_b32_e32 v70, v7
	v_mov_b32_e32 v71, v3
	v_pk_fma_f32 v[30:31], v[70:71], v[70:71], v[30:31]
	v_add_u32_e32 v49, s11, v84
	v_add_f32_e32 v20, v30, v20
	v_add_f32_e32 v20, v20, v31
	ds_bpermute_b32 v21, v72, v20
	v_mov_b32_e32 v30, v12
	v_mov_b32_e32 v31, v14
	v_mov_b32_e32 v14, v13
	v_and_b32_e32 v13, 0x1fe0, v49
	s_waitcnt lgkmcnt(0)
	v_add_f32_e32 v20, v20, v21
	ds_bpermute_b32 v21, v73, v20
	v_ashrrev_i32_e32 v34, 3, v64
	v_add_u32_e32 v57, s10, v83
	v_and_b32_e32 v87, 0xffffffe0, v34
	v_and_b32_e32 v34, 24, v57
	s_waitcnt lgkmcnt(0)
	v_add_f32_e32 v20, v20, v21
	ds_bpermute_b32 v53, v74, v20
	v_mov_b32_e32 v21, v35
	v_mov_b32_e32 v57, v35
	v_mov_b32_e32 v61, v35
	s_waitcnt lgkmcnt(0)
	v_add_f32_e32 v12, v20, v53
	ds_bpermute_b32 v20, v75, v12
	v_sub_u32_e32 v53, 0, v34
	v_lshlrev_b32_e32 v34, 1, v13
	v_xor_b32_e32 v53, v32, v53
	v_and_or_b32 v53, v53, 24, v79
	s_waitcnt lgkmcnt(0)
	v_add_f32_e32 v20, v12, v20
	ds_bpermute_b32 v49, v76, v20
	v_or_b32_e32 v12, v87, v78
	v_ashrrev_i32_e32 v13, 31, v12
	v_lshlrev_b64 v[12:13], 14, v[12:13]
	v_lshl_add_u64 v[12:13], s[62:63], 0, v[12:13]
	s_waitcnt lgkmcnt(0)
	v_add_f32_e32 v20, v20, v49
	ds_bpermute_b32 v49, v77, v20
	v_lshl_add_u64 v[12:13], v[12:13], 0, v[34:35]
	s_waitcnt lgkmcnt(0)
	v_add_f32_e32 v20, v20, v49
	v_fmamk_f32 v20, v20, 0x3a800000, v85
	v_mul_f32_e32 v49, 0x4b800000, v20
	v_cmp_gt_f32_e32 vcc, s18, v20
	s_waitcnt vmcnt(2)
	v_mov_b32_e32 v70, v22
	v_cndmask_b32_e32 v20, v20, v49, vcc
	v_rsq_f32_e32 v49, v20
	v_lshlrev_b32_e32 v20, 1, v53
	v_lshl_add_u64 v[64:65], v[12:13], 0, v[20:21]
	v_mov_b32_e32 v71, v24
	v_mul_f32_e32 v12, 0x45800000, v49
	v_cndmask_b32_e32 v12, v49, v12, vcc
	v_pk_mul_f32 v[30:31], v[30:31], v[12:13] op_sel_hi:[1,0]
	v_pk_mul_f32 v[14:15], v[14:15], v[12:13] op_sel_hi:[1,0]
	v_pk_mul_f32 v[30:31], v[70:71], v[30:31]
	s_waitcnt vmcnt(1)
	v_mov_b32_e32 v71, v28
	v_mov_b32_e32 v24, v23
	v_mov_b32_e32 v28, v27
	v_mov_b32_e32 v70, v26
	s_waitcnt vmcnt(0)
	v_mov_b32_e32 v89, v68
	v_pk_mul_f32 v[14:15], v[24:25], v[14:15]
	v_pk_add_f32 v[22:23], v[28:29], 1.0 op_sel_hi:[1,0]
	v_mov_b32_e32 v68, v67
	v_mov_b32_e32 v88, v66
	v_pk_add_f32 v[70:71], v[70:71], 1.0 op_sel_hi:[1,0]
	v_pk_fma_f32 v[14:15], v[22:23], v[14:15], v[68:69]
	v_pk_fma_f32 v[30:31], v[70:71], v[30:31], v[88:89]
	v_and_b32_sdwa v23, v15, v86 dst_sel:DWORD dst_unused:UNUSED_PAD src0_sel:WORD_1 src1_sel:DWORD
	v_and_b32_sdwa v24, v14, v86 dst_sel:DWORD dst_unused:UNUSED_PAD src0_sel:WORD_1 src1_sel:DWORD
	v_and_b32_sdwa v13, v31, v86 dst_sel:DWORD dst_unused:UNUSED_PAD src0_sel:WORD_1 src1_sel:DWORD
	v_and_b32_sdwa v22, v30, v86 dst_sel:DWORD dst_unused:UNUSED_PAD src0_sel:WORD_1 src1_sel:DWORD
	v_add3_u32 v15, v15, v23, s19
	v_add3_u32 v14, v14, v24, s19
	v_add3_u32 v22, v30, v22, s19
	v_add3_u32 v13, v31, v13, s19
	v_and_b32_e32 v15, 0xffff0000, v15
	v_and_b32_e32 v14, 0xffff0000, v14
	v_or_b32_sdwa v15, v15, v13 dst_sel:DWORD dst_unused:UNUSED_PAD src0_sel:DWORD src1_sel:WORD_1
	v_or_b32_sdwa v14, v14, v22 dst_sel:DWORD dst_unused:UNUSED_PAD src0_sel:DWORD src1_sel:WORD_1
	v_mov_b32_e32 v250, v64
	v_mov_b32_e32 v251, v65
	v_mov_b32_e32 v252, v14
	v_mov_b32_e32 v253, v15
	v_mov_b32_e32 v53, v35
	global_load_dwordx4 v[22:25], v[40:41], off
	v_lshl_add_u64 v[14:15], v[16:17], 0, v[52:53]
	global_load_dwordx4 v[26:29], v[14:15], off
	global_load_dwordx4 v[64:67], v[18:19], off offset:1024
	global_store_dwordx2 v[250:251], v[252:253], off
	v_mov_b32_e32 v15, v10
	v_mov_b32_e32 v10, v9
	v_mov_b32_e32 v14, v8
	v_pk_mul_f32 v[10:11], v[10:11], v[12:13] op_sel_hi:[1,0]
	v_or_b32_e32 v8, v87, v80
	v_pk_mul_f32 v[14:15], v[14:15], v[12:13] op_sel_hi:[1,0]
	v_ashrrev_i32_e32 v9, 31, v8
	v_lshlrev_b64 v[8:9], 14, v[8:9]
	v_lshl_add_u64 v[8:9], s[62:63], 0, v[8:9]
	v_lshl_add_u64 v[8:9], v[8:9], 0, v[34:35]
	v_lshl_add_u64 v[8:9], v[8:9], 0, v[20:21]
	s_waitcnt vmcnt(3)
	v_mov_b32_e32 v31, v24
	s_waitcnt vmcnt(2)
	v_mov_b32_e32 v69, v28
	v_mov_b32_e32 v24, v23
	v_mov_b32_e32 v28, v27
	v_mov_b32_e32 v30, v22
	v_mov_b32_e32 v68, v26
	s_waitcnt vmcnt(1)
; __device__ __forceinline__ u16 f2bf(float x) { unsigned u = __float_as_uint(x); u += 0x7fffu + ((u >> 16) & 1u); return (u16)(u >> 16); }
; __device__ __forceinline__ size_t a_off(int row, int col, int nks) { return ((size_t)((row >> 8) * nks + (col >> 5)) << 13) + ((row & 255) << 5) + swzc(row, col & 31); }
; template <int MODE>
; __device__ __forceinline__ void norm_phase(const Params& p, const float* src, const float* w, const float* modl, int sh_off, int sc_off,
;                            char* smem, int bid, int nblk) {
;     ...
;       f32x4 ww = *(const f32x4*)(w + c0);
;       f32x4 y;
;       if (MODE == 2) {
; #pragma unroll
;         for (int e = 0; e < 4; ++e) y[e] = v[i][e] * rstd * ww[e];
;         *(f32x4*)(p.out + (size_t)row * 1024 + c0) = y;
;       } else {
;         f32x4 sc = *(const f32x4*)(modl + (size_t)b * 6144 + sc_off + c0);
;         f32x4 sh = *(const f32x4*)(modl + (size_t)b * 6144 + sh_off + c0);
; #pragma unroll
;         for (int e = 0; e < 4; ++e) y[e] = v[i][e] * rstd * ww[e] * (1.f + sc[e]) + sh[e];
;         uint2 pk; pk.x = (unsigned)f2bf(y[0]) | ((unsigned)f2bf(y[1]) << 16); pk.y = (unsigned)f2bf(y[2]) | ((unsigned)f2bf(y[3]) << 16);
;         *(uint2*)(hn + a_off(row, c0, 32)) = pk;
	v_mov_b32_e32 v71, v66
	v_mov_b32_e32 v66, v65
	v_pk_mul_f32 v[10:11], v[24:25], v[10:11]
	v_pk_add_f32 v[24:25], v[28:29], 1.0 op_sel_hi:[1,0]
	v_mov_b32_e32 v70, v64
	v_pk_mul_f32 v[14:15], v[30:31], v[14:15]
	v_pk_add_f32 v[22:23], v[68:69], 1.0 op_sel_hi:[1,0]
	v_pk_fma_f32 v[10:11], v[24:25], v[10:11], v[66:67]
	v_pk_fma_f32 v[14:15], v[22:23], v[14:15], v[70:71]
	v_and_b32_sdwa v23, v11, v86 dst_sel:DWORD dst_unused:UNUSED_PAD src0_sel:WORD_1 src1_sel:DWORD
	v_and_b32_sdwa v24, v10, v86 dst_sel:DWORD dst_unused:UNUSED_PAD src0_sel:WORD_1 src1_sel:DWORD
	v_and_b32_sdwa v13, v15, v86 dst_sel:DWORD dst_unused:UNUSED_PAD src0_sel:WORD_1 src1_sel:DWORD
	v_and_b32_sdwa v22, v14, v86 dst_sel:DWORD dst_unused:UNUSED_PAD src0_sel:WORD_1 src1_sel:DWORD
	v_add3_u32 v11, v11, v23, s19
	v_add3_u32 v10, v10, v24, s19
	v_add3_u32 v14, v14, v22, s19
	v_add3_u32 v13, v15, v13, s19
	v_and_b32_e32 v11, 0xffff0000, v11
	v_and_b32_e32 v10, 0xffff0000, v10
	v_or_b32_sdwa v11, v11, v13 dst_sel:DWORD dst_unused:UNUSED_PAD src0_sel:DWORD src1_sel:WORD_1
	v_or_b32_sdwa v10, v10, v14 dst_sel:DWORD dst_unused:UNUSED_PAD src0_sel:DWORD src1_sel:WORD_1
	v_mov_b32_e32 v250, v8
	v_mov_b32_e32 v251, v9
	v_mov_b32_e32 v252, v10
	v_mov_b32_e32 v253, v11
	global_load_dwordx4 v[8:11], v[42:43], off
	v_lshl_add_u64 v[14:15], v[16:17], 0, v[56:57]
	global_load_dwordx4 v[22:25], v[14:15], off
	global_load_dwordx4 v[26:29], v[18:19], off offset:2048
	global_store_dwordx2 v[250:251], v[252:253], off
	v_mov_b32_e32 v15, v6
	v_mov_b32_e32 v6, v5
	v_mov_b32_e32 v14, v4
	v_pk_mul_f32 v[6:7], v[6:7], v[12:13] op_sel_hi:[1,0]
	v_or_b32_e32 v4, v87, v81
	v_pk_mul_f32 v[14:15], v[14:15], v[12:13] op_sel_hi:[1,0]
	v_ashrrev_i32_e32 v5, 31, v4
	v_lshlrev_b64 v[4:5], 14, v[4:5]
	v_lshl_add_u64 v[4:5], s[62:63], 0, v[4:5]
	v_lshl_add_u64 v[4:5], v[4:5], 0, v[34:35]
	v_lshl_add_u64 v[4:5], v[4:5], 0, v[20:21]
	s_waitcnt vmcnt(3)
	v_mov_b32_e32 v31, v10
	s_waitcnt vmcnt(2)
	v_mov_b32_e32 v65, v24
	v_mov_b32_e32 v10, v9
	v_mov_b32_e32 v24, v23
	v_mov_b32_e32 v30, v8
	v_mov_b32_e32 v64, v22
	s_waitcnt vmcnt(1)
	v_mov_b32_e32 v67, v28
	v_mov_b32_e32 v28, v27
	v_pk_mul_f32 v[6:7], v[6:7], v[10:11]
	v_pk_add_f32 v[10:11], v[24:25], 1.0 op_sel_hi:[1,0]
	v_mov_b32_e32 v66, v26
	v_pk_mul_f32 v[8:9], v[14:15], v[30:31]
	v_pk_add_f32 v[14:15], v[64:65], 1.0 op_sel_hi:[1,0]
	v_pk_fma_f32 v[6:7], v[6:7], v[10:11], v[28:29]
	v_pk_fma_f32 v[8:9], v[8:9], v[14:15], v[66:67]
	v_and_b32_sdwa v13, v7, v86 dst_sel:DWORD dst_unused:UNUSED_PAD src0_sel:WORD_1 src1_sel:DWORD
	v_and_b32_sdwa v14, v6, v86 dst_sel:DWORD dst_unused:UNUSED_PAD src0_sel:WORD_1 src1_sel:DWORD
	v_and_b32_sdwa v10, v9, v86 dst_sel:DWORD dst_unused:UNUSED_PAD src0_sel:WORD_1 src1_sel:DWORD
	v_and_b32_sdwa v11, v8, v86 dst_sel:DWORD dst_unused:UNUSED_PAD src0_sel:WORD_1 src1_sel:DWORD
	v_add3_u32 v7, v7, v13, s19
	v_add3_u32 v6, v6, v14, s19
	v_add3_u32 v8, v8, v11, s19
	v_add3_u32 v9, v9, v10, s19
	v_and_b32_e32 v7, 0xffff0000, v7
	v_and_b32_e32 v6, 0xffff0000, v6
	v_or_b32_sdwa v7, v7, v9 dst_sel:DWORD dst_unused:UNUSED_PAD src0_sel:DWORD src1_sel:WORD_1
	v_or_b32_sdwa v6, v6, v8 dst_sel:DWORD dst_unused:UNUSED_PAD src0_sel:DWORD src1_sel:WORD_1
	v_mov_b32_e32 v250, v4
	v_mov_b32_e32 v251, v5
	v_mov_b32_e32 v252, v6
	v_mov_b32_e32 v253, v7
	global_load_dwordx4 v[4:7], v[44:45], off
	v_lshl_add_u64 v[22:23], v[16:17], 0, v[60:61]
	global_load_dwordx4 v[8:11], v[22:23], off
	global_load_dwordx4 v[14:17], v[18:19], off offset:3072
	global_store_dwordx2 v[250:251], v[252:253], off
	v_mov_b32_e32 v18, v0
	v_or_b32_e32 v0, v87, v82
	v_mov_b32_e32 v19, v2
	v_mov_b32_e32 v2, v1
	v_ashrrev_i32_e32 v1, 31, v0
	v_lshlrev_b64 v[0:1], 14, v[0:1]
	v_lshl_add_u64 v[0:1], s[62:63], 0, v[0:1]
	v_lshl_add_u64 v[0:1], v[0:1], 0, v[34:35]
	v_lshl_add_u64 v[0:1], v[0:1], 0, v[20:21]
	v_pk_mul_f32 v[18:19], v[18:19], v[12:13] op_sel_hi:[1,0]
	v_pk_mul_f32 v[2:3], v[2:3], v[12:13] op_sel_hi:[1,0]
	s_waitcnt vmcnt(3)
	v_mov_b32_e32 v13, v6
	s_waitcnt vmcnt(2)
	v_mov_b32_e32 v21, v10
	v_mov_b32_e32 v6, v5
	v_mov_b32_e32 v10, v9
	v_mov_b32_e32 v12, v4
	v_mov_b32_e32 v20, v8
	s_waitcnt vmcnt(1)
	v_mov_b32_e32 v23, v16
	v_mov_b32_e32 v16, v15
	v_pk_mul_f32 v[2:3], v[2:3], v[6:7]
	v_pk_add_f32 v[6:7], v[10:11], 1.0 op_sel_hi:[1,0]
	v_mov_b32_e32 v22, v14
	v_pk_mul_f32 v[4:5], v[18:19], v[12:13]
	v_pk_add_f32 v[8:9], v[20:21], 1.0 op_sel_hi:[1,0]
	v_pk_fma_f32 v[2:3], v[2:3], v[6:7], v[16:17]
	v_pk_fma_f32 v[4:5], v[4:5], v[8:9], v[22:23]
	v_and_b32_sdwa v8, v3, v86 dst_sel:DWORD dst_unused:UNUSED_PAD src0_sel:WORD_1 src1_sel:DWORD
	v_and_b32_sdwa v9, v2, v86 dst_sel:DWORD dst_unused:UNUSED_PAD src0_sel:WORD_1 src1_sel:DWORD
	v_and_b32_sdwa v6, v5, v86 dst_sel:DWORD dst_unused:UNUSED_PAD src0_sel:WORD_1 src1_sel:DWORD
	v_and_b32_sdwa v7, v4, v86 dst_sel:DWORD dst_unused:UNUSED_PAD src0_sel:WORD_1 src1_sel:DWORD
	v_add3_u32 v3, v3, v8, s19
	v_add3_u32 v2, v2, v9, s19
	v_add3_u32 v4, v4, v7, s19
	v_add3_u32 v5, v5, v6, s19
	v_and_b32_e32 v3, 0xffff0000, v3
	v_and_b32_e32 v2, 0xffff0000, v2
	v_or_b32_sdwa v3, v3, v5 dst_sel:DWORD dst_unused:UNUSED_PAD src0_sel:DWORD src1_sel:WORD_1
	v_or_b32_sdwa v2, v2, v4 dst_sel:DWORD dst_unused:UNUSED_PAD src0_sel:DWORD src1_sel:WORD_1
	global_store_dwordx2 v[0:1], v[2:3], off
	s_branch .LBB0_1637

; template <int MODE>
; __device__ __forceinline__ void norm_phase(const Params& p, const float* src, const float* w, const float* modl, int sh_off, int sc_off,
;                            char* smem, int bid, int nblk) {
;     ...
;     float ss = 0.f;
; #pragma unroll
;     for (int i = 0; i < 4; ++i) ss += v[i][0] * v[i][0] + v[i][1] * v[i][1] + v[i][2] * v[i][2] + v[i][3] * v[i][3];
; #pragma unroll
;     for (int o = 32; o >= 1; o >>= 1) ss += __shfl_xor(ss, o);
;     const float rstd = rsqrtf(ss * (1.f / 1024.f) + 1e-6f);
;     const int b = row >> 13;
;     float dots[8];
;     if (MODE == 1) { for (int j = 0; j < 8; ++j) dots[j] = 0.f; }
; #pragma unroll
;     for (int i = 0; i < 4; ++i) {
;       const int c0 = i * 256 + lane * 4;
;       f32x4 ww = *(const f32x4*)(w + c0);
;       f32x4 y;
;       if (MODE == 2) {
; #pragma unroll
;         for (int e = 0; e < 4; ++e) y[e] = v[i][e] * rstd * ww[e];
;         *(f32x4*)(p.out + (size_t)row * 1024 + c0) = y;
.LBB0_2163:
	s_or_b64 exec, exec, s[0:1]
	global_load_dwordx4 v[50:53], v[34:35], off
	s_waitcnt vmcnt(0)
	v_pk_mul_f32 v[58:59], v[28:29], v[28:29]
	v_pk_mul_f32 v[60:61], v[24:25], v[24:25]
	v_pk_mul_f32 v[54:55], v[30:31], v[30:31]
	v_pk_mul_f32 v[56:57], v[26:27], v[26:27]
	v_mov_b32_e32 v64, v17
	v_mov_b32_e32 v65, v21
	v_mov_b32_e32 v70, v58
	v_mov_b32_e32 v71, v60
	v_mov_b32_e32 v60, v59
	v_mov_b32_e32 v62, v16
	v_mov_b32_e32 v63, v20
	v_mov_b32_e32 v58, v54
	v_mov_b32_e32 v59, v56
	v_mov_b32_e32 v56, v55
	v_pk_mul_f32 v[54:55], v[64:65], v[64:65]
	v_pk_add_f32 v[60:61], v[70:71], v[60:61]
	v_mov_b32_e32 v66, v18
	v_mov_b32_e32 v67, v22
	v_pk_fma_f32 v[54:55], v[62:63], v[62:63], v[54:55]
	v_pk_add_f32 v[58:59], v[58:59], v[60:61]
	v_mov_b32_e32 v68, v19
	v_mov_b32_e32 v69, v23
	v_pk_fma_f32 v[54:55], v[66:67], v[66:67], v[54:55]
	v_pk_add_f32 v[56:57], v[56:57], v[58:59]
	v_pk_fma_f32 v[54:55], v[68:69], v[68:69], v[54:55]
	v_add_f32_e32 v37, v56, v57
	v_add_f32_e32 v37, v55, v37
	v_add_f32_e32 v37, v54, v37
	ds_bpermute_b32 v49, v42, v37
	s_waitcnt lgkmcnt(0)
	v_add_f32_e32 v37, v37, v49
	ds_bpermute_b32 v49, v43, v37
	s_waitcnt lgkmcnt(0)
	v_add_f32_e32 v37, v37, v49
	ds_bpermute_b32 v49, v44, v37
	s_waitcnt lgkmcnt(0)
	v_add_f32_e32 v37, v37, v49
	ds_bpermute_b32 v49, v45, v37
	s_waitcnt lgkmcnt(0)
	v_add_f32_e32 v37, v37, v49
	ds_bpermute_b32 v49, v46, v37
	s_waitcnt lgkmcnt(0)
	v_add_f32_e32 v37, v37, v49
	ds_bpermute_b32 v49, v47, v37
	s_waitcnt lgkmcnt(0)
	v_add_f32_e32 v37, v37, v49
	v_fmamk_f32 v37, v37, 0x3a800000, v48
	v_mul_f32_e32 v49, 0x4b800000, v37
	v_cmp_gt_f32_e64 s[0:1], s8, v37
	s_nop 1
	v_cndmask_b32_e64 v37, v37, v49, s[0:1]
	v_rsq_f32_e32 v37, v37
	s_nop 0
	v_mul_f32_e32 v49, 0x45800000, v37
	v_cndmask_b32_e64 v54, v37, v49, s[0:1]
	v_pk_mul_f32 v[28:29], v[28:29], v[54:55] op_sel_hi:[1,0]
	v_pk_mul_f32 v[30:31], v[30:31], v[54:55] op_sel_hi:[1,0]
	v_pk_mul_f32 v[24:25], v[24:25], v[54:55] op_sel_hi:[1,0]
	v_pk_mul_f32 v[28:29], v[50:51], v[28:29]
	v_pk_mul_f32 v[30:31], v[52:53], v[30:31]
	v_mov_b32_e32 v250, v40
	v_mov_b32_e32 v251, v41
	v_mov_b32_e32 v252, v28
	v_mov_b32_e32 v253, v29
	v_mov_b32_e32 v254, v30
	v_mov_b32_e32 v255, v31
	global_load_dwordx4 v[28:31], v[34:35], off offset:1024
	global_store_dwordx4 v[250:251], v[252:255], off
	s_nop 1
	v_pk_mul_f32 v[26:27], v[26:27], v[54:55] op_sel_hi:[1,0]
	v_pk_mul_f32 v[20:21], v[20:21], v[54:55] op_sel_hi:[1,0]
	v_pk_mul_f32 v[22:23], v[22:23], v[54:55] op_sel_hi:[1,0]
	v_pk_mul_f32 v[16:17], v[16:17], v[54:55] op_sel_hi:[1,0]
	v_pk_mul_f32 v[18:19], v[18:19], v[54:55] op_sel_hi:[1,0]
	s_waitcnt vmcnt(1)
	v_pk_mul_f32 v[24:25], v[28:29], v[24:25]
	v_pk_mul_f32 v[26:27], v[30:31], v[26:27]
	v_mov_b32_e32 v250, v40
	v_mov_b32_e32 v251, v41
	v_mov_b32_e32 v252, v24
	v_mov_b32_e32 v253, v25
	v_mov_b32_e32 v254, v26
	v_mov_b32_e32 v255, v27
	global_load_dwordx4 v[24:27], v[34:35], off offset:2048
	global_store_dwordx4 v[250:251], v[252:255], off offset:1024
	s_nop 1
	s_waitcnt vmcnt(1)
	v_pk_mul_f32 v[20:21], v[24:25], v[20:21]
	v_pk_mul_f32 v[22:23], v[26:27], v[22:23]
	v_mov_b32_e32 v250, v40
	v_mov_b32_e32 v251, v41
	v_mov_b32_e32 v252, v20
	v_mov_b32_e32 v253, v21
	v_mov_b32_e32 v254, v22
	v_mov_b32_e32 v255, v23
	global_load_dwordx4 v[20:23], v[34:35], off offset:3072
	global_store_dwordx4 v[250:251], v[252:255], off offset:2048
	s_nop 1
	s_waitcnt vmcnt(1)
	v_pk_mul_f32 v[16:17], v[20:21], v[16:17]
	v_pk_mul_f32 v[18:19], v[22:23], v[18:19]
	global_store_dwordx4 v[40:41], v[16:19], off offset:3072
	s_and_saveexec_b64 s[0:1], vcc
	s_cbranch_execz .LBB0_2154
	global_load_dwordx4 v[16:19], v[34:35], off
	v_pk_mul_f32 v[24:25], v[8:9], v[8:9]
	v_pk_mul_f32 v[26:27], v[4:5], v[4:5]
	v_pk_mul_f32 v[20:21], v[6:7], v[6:7]
	v_pk_mul_f32 v[22:23], v[10:11], v[10:11]
	v_mov_b32_e32 v30, v1
	v_mov_b32_e32 v31, v13
	v_mov_b32_e32 v52, v26
	v_mov_b32_e32 v53, v24
	v_mov_b32_e32 v24, v27
	v_mov_b32_e32 v28, v0
	v_mov_b32_e32 v29, v12
	v_mov_b32_e32 v26, v20
	v_mov_b32_e32 v27, v22
	v_mov_b32_e32 v22, v21
	v_pk_mul_f32 v[20:21], v[30:31], v[30:31]
	v_pk_add_f32 v[24:25], v[52:53], v[24:25]
	v_mov_b32_e32 v40, v2
	v_mov_b32_e32 v41, v14
	v_pk_fma_f32 v[20:21], v[28:29], v[28:29], v[20:21]
	v_pk_add_f32 v[24:25], v[26:27], v[24:25]
	v_mov_b32_e32 v50, v3
	v_mov_b32_e32 v51, v15
	v_pk_fma_f32 v[20:21], v[40:41], v[40:41], v[20:21]
	v_pk_add_f32 v[22:23], v[22:23], v[24:25]
	v_pk_fma_f32 v[20:21], v[50:51], v[50:51], v[20:21]
	v_add_f32_e32 v22, v22, v23
	v_add_f32_e32 v20, v20, v22
	v_add_f32_e32 v20, v20, v21
	ds_bpermute_b32 v21, v42, v20
	s_waitcnt lgkmcnt(0)
	v_add_f32_e32 v20, v20, v21
	ds_bpermute_b32 v21, v43, v20
	s_waitcnt lgkmcnt(0)
	v_add_f32_e32 v20, v20, v21
	ds_bpermute_b32 v21, v44, v20
	s_waitcnt lgkmcnt(0)
	v_add_f32_e32 v20, v20, v21
	ds_bpermute_b32 v21, v45, v20
	s_waitcnt lgkmcnt(0)
	v_add_f32_e32 v20, v20, v21
	ds_bpermute_b32 v21, v46, v20
	s_waitcnt lgkmcnt(0)
	v_add_f32_e32 v20, v20, v21
	ds_bpermute_b32 v21, v47, v20
	s_waitcnt lgkmcnt(0)
	v_add_f32_e32 v20, v20, v21
	v_fmamk_f32 v20, v20, 0x3a800000, v48
	v_mul_f32_e32 v21, 0x4b800000, v20
	v_cmp_gt_f32_e32 vcc, s8, v20
	s_nop 1
	v_cndmask_b32_e32 v20, v20, v21, vcc
	v_rsq_f32_e32 v20, v20
	s_nop 0
	v_mul_f32_e32 v21, 0x45800000, v20
	v_cndmask_b32_e32 v20, v20, v21, vcc
	v_pk_mul_f32 v[4:5], v[4:5], v[20:21] op_sel_hi:[1,0]
	v_pk_mul_f32 v[6:7], v[6:7], v[20:21] op_sel_hi:[1,0]
	v_pk_mul_f32 v[8:9], v[8:9], v[20:21] op_sel_hi:[1,0]
	s_waitcnt vmcnt(0)
	v_pk_mul_f32 v[4:5], v[16:17], v[4:5]
	v_pk_mul_f32 v[6:7], v[18:19], v[6:7]
	v_mov_b32_e32 v250, v38
	v_mov_b32_e32 v251, v39
	v_mov_b32_e32 v252, v4
	v_mov_b32_e32 v253, v5
	v_mov_b32_e32 v254, v6
	v_mov_b32_e32 v255, v7
	global_load_dwordx4 v[4:7], v[34:35], off offset:1024
	global_store_dwordx4 v[250:251], v[252:255], off
	s_nop 1
	v_pk_mul_f32 v[10:11], v[10:11], v[20:21] op_sel_hi:[1,0]
	v_pk_mul_f32 v[0:1], v[0:1], v[20:21] op_sel_hi:[1,0]
	v_pk_mul_f32 v[2:3], v[2:3], v[20:21] op_sel_hi:[1,0]
	s_waitcnt vmcnt(1)
	v_pk_mul_f32 v[4:5], v[4:5], v[8:9]
	v_pk_mul_f32 v[6:7], v[6:7], v[10:11]
	v_mov_b32_e32 v250, v38
	v_mov_b32_e32 v251, v39
	v_mov_b32_e32 v252, v4
	v_mov_b32_e32 v253, v5
	v_mov_b32_e32 v254, v6
	v_mov_b32_e32 v255, v7
	global_load_dwordx4 v[4:7], v[34:35], off offset:2048
	global_store_dwordx4 v[250:251], v[252:255], off offset:1024
	s_nop 1
	s_waitcnt vmcnt(1)
	v_pk_mul_f32 v[0:1], v[4:5], v[0:1]
	v_pk_mul_f32 v[2:3], v[6:7], v[2:3]
	v_mov_b32_e32 v250, v38
	v_mov_b32_e32 v251, v39
	v_mov_b32_e32 v252, v0
	v_mov_b32_e32 v253, v1
	v_mov_b32_e32 v254, v2
	v_mov_b32_e32 v255, v3
	global_load_dwordx4 v[0:3], v[34:35], off offset:3072
	global_store_dwordx4 v[250:251], v[252:255], off offset:2048
	s_nop 1
	v_pk_mul_f32 v[4:5], v[12:13], v[20:21] op_sel_hi:[1,0]
	v_pk_mul_f32 v[6:7], v[14:15], v[20:21] op_sel_hi:[1,0]
	s_waitcnt vmcnt(1)
	v_pk_mul_f32 v[0:1], v[0:1], v[4:5]
	v_pk_mul_f32 v[2:3], v[2:3], v[6:7]
	global_store_dwordx4 v[38:39], v[0:3], off offset:3072
	s_branch .LBB0_2154
